# GEMM outputs that the next phase re-reads (ybuf from down/outproj/pool GEMM) stored with the default cache policy instead of non-temporal
# speedup vs baseline: 1.0815x; 1.0050x over previous
.LBB0_2002:
	s_add_i32 s39, s38, 1
	s_cmp_lt_u32 s38, 7
	s_cselect_b64 s[40:41], -1, 0
	s_add_u32 s38, s35, s2
	s_addc_u32 s44, s36, s3
	s_add_u32 s45, s31, s2
	s_addc_u32 s46, s34, s3
	s_and_b64 s[42:43], s[40:41], exec
	s_cselect_b32 s43, s44, s46
	s_cselect_b32 s42, s38, s45
	s_add_i32 s38, s37, 0x10000
	s_and_b32 s44, s38, 0x10000
	s_add_i32 s45, s44, s8
	s_and_b64 s[40:41], s[40:41], exec
	v_lshl_add_u64 v[148:149], v[128:129], 0, s[2:3]
	s_mov_b32 m0, s45
	s_cselect_b32 s40, 10, 11
	global_load_lds_dwordx4 v[148:149], off
	v_lshl_or_b32 v132, v139, s40, v138
	s_add_i32 m0, s45, 0x8000
	s_add_i32 s41, s44, s11
	global_load_lds_dwordx4 v132, s[42:43]
	v_lshl_add_u64 v[148:149], v[130:131], 0, s[2:3]
	s_mov_b32 m0, s41
	v_lshl_or_b32 v132, v140, s40, v138
	global_load_lds_dwordx4 v[148:149], off
	s_add_i32 m0, s41, 0x8000
	s_add_i32 s41, s44, s12
	global_load_lds_dwordx4 v132, s[42:43]
	v_lshl_add_u64 v[148:149], v[134:135], 0, s[2:3]
	s_mov_b32 m0, s41
	v_lshl_or_b32 v132, v144, s40, v138
	global_load_lds_dwordx4 v[148:149], off
	s_add_i32 m0, s41, 0x8000
	s_add_i32 s41, s44, s13
	global_load_lds_dwordx4 v132, s[42:43]
	v_lshl_add_u64 v[148:149], v[136:137], 0, s[2:3]
	s_mov_b32 m0, s41
	v_lshl_or_b32 v132, v145, s40, v138
	global_load_lds_dwordx4 v[148:149], off
	s_add_i32 m0, s41, 0x8000
	s_and_b32 s37, s37, 0x10000
	global_load_lds_dwordx4 v132, s[42:43]
	v_or_b32_e32 v132, s37, v146
	v_add_u32_e32 v147, v132, v143
	v_add_u32_e32 v132, v132, v141
	ds_read_b128 v[148:151], v147 offset:32768
	ds_read_b128 v[152:155], v147 offset:34816
	ds_read_b128 v[156:159], v147 offset:36864
	ds_read_b128 v[160:163], v147 offset:38912
	ds_read_b128 v[164:167], v132
	ds_read_b128 v[168:171], v132 offset:2048
	ds_read_b128 v[172:175], v132 offset:4096
	ds_read_b128 v[176:179], v132 offset:6144
	ds_read_b128 v[180:183], v132 offset:8192
	ds_read_b128 v[186:189], v132 offset:10240
	ds_read_b128 v[190:193], v132 offset:12288
	ds_read_b128 v[194:197], v132 offset:14336
	s_waitcnt lgkmcnt(0)
	v_mfma_f32_16x16x32_bf16 v[124:127], v[164:167], v[148:151], v[124:127]
	v_mfma_f32_16x16x32_bf16 v[120:123], v[164:167], v[152:155], v[120:123]
	v_mfma_f32_16x16x32_bf16 v[116:119], v[164:167], v[156:159], v[116:119]
	v_mfma_f32_16x16x32_bf16 v[112:115], v[164:167], v[160:163], v[112:115]
	v_mfma_f32_16x16x32_bf16 v[108:111], v[168:171], v[148:151], v[108:111]
	v_mfma_f32_16x16x32_bf16 v[104:107], v[168:171], v[152:155], v[104:107]
	v_mfma_f32_16x16x32_bf16 v[100:103], v[168:171], v[156:159], v[100:103]
	v_mfma_f32_16x16x32_bf16 v[96:99], v[168:171], v[160:163], v[96:99]
	v_mfma_f32_16x16x32_bf16 v[88:91], v[172:175], v[148:151], v[88:91]
	v_mfma_f32_16x16x32_bf16 v[80:83], v[172:175], v[152:155], v[80:83]
	v_mfma_f32_16x16x32_bf16 v[76:79], v[172:175], v[156:159], v[76:79]
	v_mfma_f32_16x16x32_bf16 v[72:75], v[172:175], v[160:163], v[72:75]
	v_mfma_f32_16x16x32_bf16 v[68:71], v[176:179], v[148:151], v[68:71]
	v_mfma_f32_16x16x32_bf16 v[64:67], v[176:179], v[152:155], v[64:67]
	v_mfma_f32_16x16x32_bf16 v[60:63], v[176:179], v[156:159], v[60:63]
	v_mfma_f32_16x16x32_bf16 v[56:59], v[176:179], v[160:163], v[56:59]
	v_or_b32_e32 v132, s37, v142
	v_add_u32_e32 v147, v132, v143
	v_add_u32_e32 v132, v132, v141
	ds_read_b128 v[164:167], v147 offset:32768
	ds_read_b128 v[168:171], v147 offset:34816
	ds_read_b128 v[172:175], v147 offset:36864
	ds_read_b128 v[176:179], v147 offset:38912
	ds_read_b128 v[198:201], v132
	ds_read_b128 v[202:205], v132 offset:2048
	ds_read_b128 v[206:209], v132 offset:4096
	ds_read_b128 v[210:213], v132 offset:6144
	v_mfma_f32_16x16x32_bf16 v[52:55], v[180:183], v[148:151], v[52:55]
	v_mfma_f32_16x16x32_bf16 v[48:51], v[180:183], v[152:155], v[48:51]
	v_mfma_f32_16x16x32_bf16 v[44:47], v[180:183], v[156:159], v[44:47]
	v_mfma_f32_16x16x32_bf16 v[40:43], v[180:183], v[160:163], v[40:43]
	v_mfma_f32_16x16x32_bf16 v[36:39], v[186:189], v[148:151], v[36:39]
	v_mfma_f32_16x16x32_bf16 v[32:35], v[186:189], v[152:155], v[32:35]
	v_mfma_f32_16x16x32_bf16 v[28:31], v[186:189], v[156:159], v[28:31]
	v_mfma_f32_16x16x32_bf16 v[24:27], v[186:189], v[160:163], v[24:27]
	v_mfma_f32_16x16x32_bf16 v[20:23], v[190:193], v[148:151], v[20:23]
	v_mfma_f32_16x16x32_bf16 v[16:19], v[190:193], v[152:155], v[16:19]
	v_mfma_f32_16x16x32_bf16 v[12:15], v[190:193], v[156:159], v[12:15]
	v_mfma_f32_16x16x32_bf16 v[8:11], v[190:193], v[160:163], v[8:11]
	v_mfma_f32_16x16x32_bf16 v[4:7], v[194:197], v[148:151], v[4:7]
	v_mfma_f32_16x16x32_bf16 v[0:3], v[194:197], v[152:155], v[0:3]
	v_mfma_f32_16x16x32_bf16 v[92:95], v[194:197], v[156:159], v[92:95]
	v_mfma_f32_16x16x32_bf16 v[84:87], v[194:197], v[160:163], v[84:87]
	ds_read_b128 v[148:151], v132 offset:8192
	ds_read_b128 v[152:155], v132 offset:10240
	ds_read_b128 v[156:159], v132 offset:12288
	ds_read_b128 v[160:163], v132 offset:14336
	s_waitcnt lgkmcnt(0)
	v_mfma_f32_16x16x32_bf16 v[124:127], v[198:201], v[164:167], v[124:127]
	v_mfma_f32_16x16x32_bf16 v[120:123], v[198:201], v[168:171], v[120:123]
	v_mfma_f32_16x16x32_bf16 v[116:119], v[198:201], v[172:175], v[116:119]
	v_mfma_f32_16x16x32_bf16 v[112:115], v[198:201], v[176:179], v[112:115]
	v_mfma_f32_16x16x32_bf16 v[108:111], v[202:205], v[164:167], v[108:111]
	v_mfma_f32_16x16x32_bf16 v[104:107], v[202:205], v[168:171], v[104:107]
	v_mfma_f32_16x16x32_bf16 v[100:103], v[202:205], v[172:175], v[100:103]
	v_mfma_f32_16x16x32_bf16 v[96:99], v[202:205], v[176:179], v[96:99]
	v_mfma_f32_16x16x32_bf16 v[88:91], v[206:209], v[164:167], v[88:91]
	v_mfma_f32_16x16x32_bf16 v[80:83], v[206:209], v[168:171], v[80:83]
	v_mfma_f32_16x16x32_bf16 v[76:79], v[206:209], v[172:175], v[76:79]
	v_mfma_f32_16x16x32_bf16 v[72:75], v[206:209], v[176:179], v[72:75]
	v_mfma_f32_16x16x32_bf16 v[68:71], v[210:213], v[164:167], v[68:71]
	v_mfma_f32_16x16x32_bf16 v[64:67], v[210:213], v[168:171], v[64:67]
	v_mfma_f32_16x16x32_bf16 v[60:63], v[210:213], v[172:175], v[60:63]
	v_mfma_f32_16x16x32_bf16 v[56:59], v[210:213], v[176:179], v[56:59]
	v_mfma_f32_16x16x32_bf16 v[52:55], v[148:151], v[164:167], v[52:55]
	s_waitcnt vmcnt(0)
	s_waitcnt lgkmcnt(0)
	s_barrier
	v_mfma_f32_16x16x32_bf16 v[48:51], v[148:151], v[168:171], v[48:51]
	s_add_u32 s2, s2, 0x80
	s_addc_u32 s3, s3, 0
	v_mfma_f32_16x16x32_bf16 v[44:47], v[148:151], v[172:175], v[44:47]
	s_cmpk_lg_i32 s2, 0xb80
	s_mov_b32 s37, s38
	s_mov_b32 s38, s39
	v_mfma_f32_16x16x32_bf16 v[40:43], v[148:151], v[176:179], v[40:43]
	v_mfma_f32_16x16x32_bf16 v[36:39], v[152:155], v[164:167], v[36:39]
	v_mfma_f32_16x16x32_bf16 v[32:35], v[152:155], v[168:171], v[32:35]
	v_mfma_f32_16x16x32_bf16 v[28:31], v[152:155], v[172:175], v[28:31]
	v_mfma_f32_16x16x32_bf16 v[24:27], v[152:155], v[176:179], v[24:27]
	v_mfma_f32_16x16x32_bf16 v[20:23], v[156:159], v[164:167], v[20:23]
	v_mfma_f32_16x16x32_bf16 v[16:19], v[156:159], v[168:171], v[16:19]
	v_mfma_f32_16x16x32_bf16 v[12:15], v[156:159], v[172:175], v[12:15]
	v_mfma_f32_16x16x32_bf16 v[8:11], v[156:159], v[176:179], v[8:11]
	v_mfma_f32_16x16x32_bf16 v[4:7], v[160:163], v[164:167], v[4:7]
	v_mfma_f32_16x16x32_bf16 v[0:3], v[160:163], v[168:171], v[0:3]
	v_mfma_f32_16x16x32_bf16 v[92:95], v[160:163], v[172:175], v[92:95]
	v_mfma_f32_16x16x32_bf16 v[84:87], v[160:163], v[176:179], v[84:87]
	s_cbranch_scc1 .LBB0_2002
	v_add3_u32 v132, v141, v146, s28
	ds_read_b128 v[128:131], v132 offset:14336
	ds_read_b128 v[134:137], v132 offset:12288
	ds_read_b128 v[148:151], v132 offset:10240
	ds_read_b128 v[152:155], v132 offset:8192
	ds_read_b128 v[156:159], v132 offset:6144
	ds_read_b128 v[160:163], v132 offset:4096
	ds_read_b128 v[164:167], v132 offset:2048
	ds_read_b128 v[168:171], v132
	v_add3_u32 v132, v143, v146, s27
	ds_read_b128 v[144:147], v132 offset:6144
	ds_read_b128 v[172:175], v132 offset:4096
	ds_read_b128 v[176:179], v132 offset:2048
	ds_read_b128 v[180:183], v132
	s_waitcnt lgkmcnt(0)
	v_mfma_f32_16x16x32_bf16 v[124:127], v[168:171], v[180:183], v[124:127]
	v_mfma_f32_16x16x32_bf16 v[120:123], v[168:171], v[176:179], v[120:123]
	v_mfma_f32_16x16x32_bf16 v[116:119], v[168:171], v[172:175], v[116:119]
	v_mfma_f32_16x16x32_bf16 v[112:115], v[168:171], v[144:147], v[112:115]
	v_mfma_f32_16x16x32_bf16 v[108:111], v[164:167], v[180:183], v[108:111]
	v_mfma_f32_16x16x32_bf16 v[104:107], v[164:167], v[176:179], v[104:107]
	v_mfma_f32_16x16x32_bf16 v[100:103], v[164:167], v[172:175], v[100:103]
	v_mfma_f32_16x16x32_bf16 v[96:99], v[164:167], v[144:147], v[96:99]
	v_mfma_f32_16x16x32_bf16 v[88:91], v[160:163], v[180:183], v[88:91]
	v_mfma_f32_16x16x32_bf16 v[80:83], v[160:163], v[176:179], v[80:83]
	v_mfma_f32_16x16x32_bf16 v[76:79], v[160:163], v[172:175], v[76:79]
	v_mfma_f32_16x16x32_bf16 v[72:75], v[160:163], v[144:147], v[72:75]
	v_mfma_f32_16x16x32_bf16 v[68:71], v[156:159], v[180:183], v[68:71]
	v_mfma_f32_16x16x32_bf16 v[64:67], v[156:159], v[176:179], v[64:67]
	v_mfma_f32_16x16x32_bf16 v[56:59], v[156:159], v[144:147], v[56:59]
	v_mfma_f32_16x16x32_bf16 v[160:163], v[156:159], v[172:175], v[60:63]
	s_nop 2
	v_add3_u32 v60, v143, v142, s27
	ds_read_b128 v[156:159], v60
	ds_read_b128 v[164:167], v60 offset:2048
	ds_read_b128 v[168:171], v60 offset:4096
	ds_read_b128 v[186:189], v60 offset:6144
	v_add3_u32 v60, v141, v142, s28
	ds_read_b128 v[138:141], v60
	ds_read_b128 v[190:193], v60 offset:2048
	ds_read_b128 v[194:197], v60 offset:4096
	ds_read_b128 v[198:201], v60 offset:6144
	v_mfma_f32_16x16x32_bf16 v[44:47], v[152:155], v[172:175], v[44:47]
	v_mfma_f32_16x16x32_bf16 v[32:35], v[148:151], v[176:179], v[32:35]
	v_mfma_f32_16x16x32_bf16 v[28:31], v[148:151], v[172:175], v[28:31]
	v_mfma_f32_16x16x32_bf16 v[16:19], v[134:137], v[176:179], v[16:19]
	v_mfma_f32_16x16x32_bf16 v[202:205], v[152:155], v[180:183], v[52:55]
	v_mfma_f32_16x16x32_bf16 v[206:209], v[152:155], v[176:179], v[48:51]
	v_mfma_f32_16x16x32_bf16 v[152:155], v[152:155], v[144:147], v[40:43]
	v_mfma_f32_16x16x32_bf16 v[210:213], v[148:151], v[180:183], v[36:39]
	v_mfma_f32_16x16x32_bf16 v[148:151], v[148:151], v[144:147], v[24:27]
	v_mfma_f32_16x16x32_bf16 v[214:217], v[134:137], v[180:183], v[20:23]
	v_mfma_f32_16x16x32_bf16 v[218:221], v[134:137], v[172:175], v[12:15]
	v_mfma_f32_16x16x32_bf16 v[222:225], v[134:137], v[144:147], v[8:11]
	v_mfma_f32_16x16x32_bf16 v[180:183], v[128:131], v[180:183], v[4:7]
	v_mfma_f32_16x16x32_bf16 v[176:179], v[128:131], v[176:179], v[0:3]
	v_mfma_f32_16x16x32_bf16 v[172:175], v[128:131], v[172:175], v[92:95]
	v_mfma_f32_16x16x32_bf16 v[142:145], v[128:131], v[144:147], v[84:87]
	s_nop 0
	ds_read_b128 v[0:3], v60 offset:8192
	ds_read_b128 v[128:131], v60 offset:10240
	ds_read_b128 v[226:229], v60 offset:12288
	ds_read_b128 v[230:233], v60 offset:14336
	s_waitcnt lgkmcnt(0)
	v_mfma_f32_16x16x32_bf16 v[124:127], v[138:141], v[156:159], v[124:127]
	v_mfma_f32_16x16x32_bf16 v[92:95], v[138:141], v[164:167], v[120:123]
	v_mfma_f32_16x16x32_bf16 v[60:63], v[138:141], v[168:171], v[116:119]
	v_mfma_f32_16x16x32_bf16 v[24:27], v[138:141], v[186:189], v[112:115]
	v_mfma_f32_16x16x32_bf16 v[120:123], v[190:193], v[156:159], v[108:111]
	v_mfma_f32_16x16x32_bf16 v[84:87], v[190:193], v[164:167], v[104:107]
	v_mfma_f32_16x16x32_bf16 v[52:55], v[190:193], v[168:171], v[100:103]
	v_mfma_f32_16x16x32_bf16 v[20:23], v[190:193], v[186:189], v[96:99]
	v_mfma_f32_16x16x32_bf16 v[112:115], v[194:197], v[156:159], v[88:91]
	v_mfma_f32_16x16x32_bf16 v[80:83], v[194:197], v[164:167], v[80:83]
	v_mfma_f32_16x16x32_bf16 v[48:51], v[194:197], v[168:171], v[76:79]
	v_mfma_f32_16x16x32_bf16 v[12:15], v[194:197], v[186:189], v[72:75]
	v_mfma_f32_16x16x32_bf16 v[108:111], v[198:201], v[156:159], v[68:71]
	v_mfma_f32_16x16x32_bf16 v[76:79], v[198:201], v[164:167], v[64:67]
	v_mfma_f32_16x16x32_bf16 v[40:43], v[198:201], v[168:171], v[160:163]
	v_mfma_f32_16x16x32_bf16 v[8:11], v[198:201], v[186:189], v[56:59]
	s_waitcnt vmcnt(0)
	v_mov_b32_e32 v135, v184
	v_mfma_f32_16x16x32_bf16 v[64:67], v[128:131], v[164:167], v[32:35]
	s_waitcnt lgkmcnt(0)
	s_barrier
	v_mfma_f32_16x16x32_bf16 v[32:35], v[128:131], v[168:171], v[28:31]
	v_cvt_pk_bf16_f32 v132, v124, v125
	v_cvt_pk_bf16_f32 v134, v126, v127
	v_mfma_f32_16x16x32_bf16 v[104:107], v[0:3], v[156:159], v[202:205]
	v_and_b32_e32 v28, 16, v135
	v_cmp_eq_u32_e64 s[2:3], 0, v28
	v_cmp_ne_u32_e32 vcc, 0, v28
	v_mfma_f32_16x16x32_bf16 v[68:71], v[0:3], v[164:167], v[206:209]
	v_cvt_pk_bf16_f32 v136, v120, v121
	v_cvt_pk_bf16_f32 v137, v122, v123
	v_mfma_f32_16x16x32_bf16 v[36:39], v[0:3], v[168:171], v[44:47]
	v_mfma_f32_16x16x32_bf16 v[4:7], v[0:3], v[186:189], v[152:155]
	v_mfma_f32_16x16x32_bf16 v[100:103], v[128:131], v[156:159], v[210:213]
	v_mfma_f32_16x16x32_bf16 v[0:3], v[128:131], v[186:189], v[148:151]
	v_mov_b32_e32 v128, v132
	v_mov_b32_e32 v130, v136
	v_mov_b32_e32 v129, v134
	v_mfma_f32_16x16x32_bf16 v[96:99], v[226:229], v[156:159], v[214:217]
	v_mov_b32_e32 v131, v137
	v_permlane16_swap_b32_e32 v128, v130
	v_mfma_f32_16x16x32_bf16 v[72:75], v[226:229], v[164:167], v[16:19]
	v_permlane16_swap_b32_e32 v129, v131
	v_mfma_f32_16x16x32_bf16 v[44:47], v[226:229], v[168:171], v[218:221]
	v_mfma_f32_16x16x32_bf16 v[16:19], v[226:229], v[186:189], v[222:225]
	v_mfma_f32_16x16x32_bf16 v[116:119], v[230:233], v[156:159], v[180:183]
	v_mfma_f32_16x16x32_bf16 v[88:91], v[230:233], v[164:167], v[176:179]
	v_mfma_f32_16x16x32_bf16 v[56:59], v[230:233], v[168:171], v[172:175]
	v_mfma_f32_16x16x32_bf16 v[28:31], v[230:233], v[186:189], v[142:145]
	s_and_saveexec_b64 s[12:13], vcc
	s_xor_b64 s[12:13], exec, s[12:13]
	v_mov_b32_e32 v131, v137
	v_mov_b32_e32 v130, v136
	s_andn2_saveexec_b64 s[12:13], s[12:13]
	v_mov_b32_e32 v128, v132
	v_mov_b32_e32 v129, v134
	s_or_b64 exec, exec, s[12:13]
	v_ashrrev_i32_e32 v134, 8, v135
	v_bfe_u32 v132, v135, 4, 2
	v_and_b32_e32 v135, 0xcf, v135
	v_lshlrev_b32_e32 v136, 2, v132
	v_lshl_or_b32 v138, s10, 8, v135
	v_add_u32_e32 v137, 12, v136
	v_ashrrev_i32_e32 v139, 31, v138
	v_cndmask_b32_e64 v136, v137, v136, s[2:3]
	v_lshlrev_b64 v[140:141], 11, v[138:139]
	s_lshl_b32 s8, s30, 8
	v_lshl_or_b32 v136, v134, 7, v136
	v_lshl_add_u64 v[140:141], s[4:5], 0, v[140:141]
	v_lshl_add_u64 v[140:141], s[8:9], 1, v[140:141]
	v_ashrrev_i32_e32 v137, 31, v136
	v_lshl_add_u64 v[140:141], v[136:137], 1, v[140:141]
	v_cvt_pk_bf16_f32 v135, v112, v113
	v_cvt_pk_bf16_f32 v142, v114, v115
	v_cvt_pk_bf16_f32 v143, v108, v109
	v_cvt_pk_bf16_f32 v144, v110, v111
	global_store_dwordx4 v[140:141], v[128:131], off
	s_nop 1
	v_mov_b32_e32 v130, v143
	v_mov_b32_e32 v128, v135
	v_mov_b32_e32 v131, v144
	v_mov_b32_e32 v129, v142
	v_permlane16_swap_b32_e32 v128, v130
	s_nop 0
	v_permlane16_swap_b32_e32 v129, v131
	s_and_saveexec_b64 s[2:3], vcc
	s_xor_b64 s[2:3], exec, s[2:3]
	v_mov_b32_e32 v131, v144
	v_mov_b32_e32 v130, v143
	s_andn2_saveexec_b64 s[2:3], s[2:3]
	v_mov_b32_e32 v128, v135
	v_mov_b32_e32 v129, v142
	s_or_b64 exec, exec, s[2:3]
	v_cvt_pk_bf16_f32 v135, v104, v105
	v_cvt_pk_bf16_f32 v142, v106, v107
	v_cvt_pk_bf16_f32 v143, v100, v101
	v_cvt_pk_bf16_f32 v144, v102, v103
	global_store_dwordx4 v[140:141], v[128:131], off offset:64
	s_nop 1
	v_mov_b32_e32 v130, v143
	v_mov_b32_e32 v128, v135
	v_mov_b32_e32 v131, v144
	v_mov_b32_e32 v129, v142
	v_permlane16_swap_b32_e32 v128, v130
	s_nop 0
	v_permlane16_swap_b32_e32 v129, v131
	s_and_saveexec_b64 s[2:3], vcc
	s_xor_b64 s[2:3], exec, s[2:3]
	v_mov_b32_e32 v131, v144
	v_mov_b32_e32 v130, v143
	s_andn2_saveexec_b64 s[2:3], s[2:3]
	v_mov_b32_e32 v128, v135
	v_mov_b32_e32 v129, v142
	s_or_b64 exec, exec, s[2:3]
	v_cvt_pk_bf16_f32 v135, v96, v97
	v_cvt_pk_bf16_f32 v142, v98, v99
	v_cvt_pk_bf16_f32 v143, v116, v117
	v_cvt_pk_bf16_f32 v144, v118, v119
	global_store_dwordx4 v[140:141], v[128:131], off offset:128
	s_nop 1
	v_mov_b32_e32 v130, v143
	v_mov_b32_e32 v128, v135
	v_mov_b32_e32 v131, v144
	v_mov_b32_e32 v129, v142
	v_permlane16_swap_b32_e32 v128, v130
	s_nop 0
	v_permlane16_swap_b32_e32 v129, v131
	s_and_saveexec_b64 s[2:3], vcc
	s_xor_b64 s[2:3], exec, s[2:3]
	v_mov_b32_e32 v131, v144
	v_mov_b32_e32 v130, v143
	s_andn2_saveexec_b64 s[2:3], s[2:3]
	v_mov_b32_e32 v128, v135
	v_mov_b32_e32 v129, v142
	s_or_b64 exec, exec, s[2:3]
	v_mul_f32_e32 v125, v125, v125
	v_mul_f32_e32 v113, v113, v113
	v_fmac_f32_e32 v125, v124, v124
	v_fmac_f32_e32 v113, v112, v112
	v_mul_f32_e32 v105, v105, v105
	v_fmac_f32_e32 v125, v126, v126
	v_fmac_f32_e32 v113, v114, v114
	v_fmac_f32_e32 v105, v104, v104
	v_mul_f32_e32 v97, v97, v97
	v_fmac_f32_e32 v125, v127, v127
	v_fmac_f32_e32 v113, v115, v115
	v_fmac_f32_e32 v105, v106, v106
	v_fmac_f32_e32 v97, v96, v96
	v_fmac_f32_e32 v125, v120, v120
	v_fmac_f32_e32 v113, v108, v108
	v_fmac_f32_e32 v105, v107, v107
	v_fmac_f32_e32 v97, v98, v98
	v_fmac_f32_e32 v125, v121, v121
	v_fmac_f32_e32 v113, v109, v109
	v_fmac_f32_e32 v105, v100, v100
	v_fmac_f32_e32 v97, v99, v99
	v_fmac_f32_e32 v125, v122, v122
	v_fmac_f32_e32 v113, v110, v110
	v_fmac_f32_e32 v105, v101, v101
	v_fmac_f32_e32 v97, v116, v116
	v_fmac_f32_e32 v125, v123, v123
	v_fmac_f32_e32 v113, v111, v111
	v_fmac_f32_e32 v105, v102, v102
	v_fmac_f32_e32 v97, v117, v117
	v_add_f32_e32 v108, v125, v113
	v_fmac_f32_e32 v105, v103, v103
	v_fmac_f32_e32 v97, v118, v118
	v_add_f32_e32 v100, v108, v105
	v_fmac_f32_e32 v97, v119, v119
	v_add_f32_e32 v96, v100, v97
	v_mov_b32_e32 v97, v96
	s_nop 1
	v_permlane16_swap_b32_e32 v96, v97
	v_add_f32_e32 v96, v96, v97
	v_mov_b32_e32 v97, v96
	v_cmp_eq_u32_e64 s[2:3], 0, v132
	v_ashrrev_i32_e32 v135, 31, v134
	v_permlane32_swap_b32_e32 v96, v97
	global_store_dwordx4 v[140:141], v[128:131], off offset:192
	s_and_saveexec_b64 s[12:13], s[2:3]
	s_cbranch_execz .LBB0_2021
	v_add_f32_e32 v98, v96, v97
	v_lshlrev_b64 v[96:97], 5, v[138:139]
	s_lshl_b32 s34, s30, 1
	s_mov_b32 s35, s9
	v_lshl_add_u64 v[96:97], s[6:7], 0, v[96:97]
	v_lshl_add_u64 v[96:97], s[34:35], 2, v[96:97]
	v_lshl_add_u64 v[96:97], v[134:135], 2, v[96:97]
	global_store_dword v[96:97], v98, off
.LBB0_2021:
	s_or_b64 exec, exec, s[12:13]
	v_cvt_pk_bf16_f32 v100, v92, v93
	v_cvt_pk_bf16_f32 v101, v94, v95
	v_cvt_pk_bf16_f32 v102, v84, v85
	v_cvt_pk_bf16_f32 v103, v86, v87
	v_mov_b32_e32 v98, v102
	v_mov_b32_e32 v96, v100
	v_mov_b32_e32 v97, v101
	v_mov_b32_e32 v99, v103
	v_permlane16_swap_b32_e32 v96, v98
	s_nop 0
	v_permlane16_swap_b32_e32 v97, v99
	s_and_saveexec_b64 s[12:13], vcc
	s_xor_b64 s[12:13], exec, s[12:13]
	v_mov_b32_e32 v99, v103
	v_mov_b32_e32 v98, v102
	s_andn2_saveexec_b64 s[12:13], s[12:13]
	v_mov_b32_e32 v96, v100
	v_mov_b32_e32 v97, v101
	s_or_b64 exec, exec, s[12:13]
	v_or_b32_e32 v100, 16, v138
	v_ashrrev_i32_e32 v101, 31, v100
	v_lshlrev_b64 v[102:103], 11, v[100:101]
	v_lshl_add_u64 v[102:103], s[4:5], 0, v[102:103]
	v_lshl_add_u64 v[102:103], s[8:9], 1, v[102:103]
	v_lshl_add_u64 v[102:103], v[136:137], 1, v[102:103]
	v_cvt_pk_bf16_f32 v104, v80, v81
	v_cvt_pk_bf16_f32 v105, v82, v83
	v_cvt_pk_bf16_f32 v106, v76, v77
	v_cvt_pk_bf16_f32 v107, v78, v79
	global_store_dwordx4 v[102:103], v[96:99], off
	s_nop 1
	v_mov_b32_e32 v96, v104
	v_mov_b32_e32 v98, v106
	v_mov_b32_e32 v99, v107
	v_mov_b32_e32 v97, v105
	v_permlane16_swap_b32_e32 v96, v98
	s_nop 0
	v_permlane16_swap_b32_e32 v97, v99
	s_and_saveexec_b64 s[12:13], vcc
	s_xor_b64 s[12:13], exec, s[12:13]
	v_mov_b32_e32 v99, v107
	v_mov_b32_e32 v98, v106
	s_andn2_saveexec_b64 s[12:13], s[12:13]
	v_mov_b32_e32 v96, v104
	v_mov_b32_e32 v97, v105
	s_or_b64 exec, exec, s[12:13]
	v_cvt_pk_bf16_f32 v104, v68, v69
	v_cvt_pk_bf16_f32 v105, v70, v71
	v_cvt_pk_bf16_f32 v106, v64, v65
	v_cvt_pk_bf16_f32 v107, v66, v67
	global_store_dwordx4 v[102:103], v[96:99], off offset:64
	s_nop 1
	v_mov_b32_e32 v96, v104
	v_mov_b32_e32 v98, v106
	v_mov_b32_e32 v99, v107
	v_mov_b32_e32 v97, v105
	v_permlane16_swap_b32_e32 v96, v98
	s_nop 0
	v_permlane16_swap_b32_e32 v97, v99
	s_and_saveexec_b64 s[12:13], vcc
	s_xor_b64 s[12:13], exec, s[12:13]
	v_mov_b32_e32 v99, v107
	v_mov_b32_e32 v98, v106
	s_andn2_saveexec_b64 s[12:13], s[12:13]
	v_mov_b32_e32 v96, v104
	v_mov_b32_e32 v97, v105
	s_or_b64 exec, exec, s[12:13]
	v_cvt_pk_bf16_f32 v104, v72, v73
	v_cvt_pk_bf16_f32 v105, v74, v75
	v_cvt_pk_bf16_f32 v106, v88, v89
	v_cvt_pk_bf16_f32 v107, v90, v91
	global_store_dwordx4 v[102:103], v[96:99], off offset:128
	s_nop 1
	v_mov_b32_e32 v96, v104
	v_mov_b32_e32 v98, v106
	v_mov_b32_e32 v99, v107
	v_mov_b32_e32 v97, v105
	v_permlane16_swap_b32_e32 v96, v98
	s_nop 0
	v_permlane16_swap_b32_e32 v97, v99
	s_and_saveexec_b64 s[12:13], vcc
	s_xor_b64 s[12:13], exec, s[12:13]
	v_mov_b32_e32 v99, v107
	v_mov_b32_e32 v98, v106
	s_andn2_saveexec_b64 s[12:13], s[12:13]
	v_mov_b32_e32 v96, v104
	v_mov_b32_e32 v97, v105
	s_or_b64 exec, exec, s[12:13]
	v_mul_f32_e32 v69, v69, v69
	v_fmac_f32_e32 v69, v68, v68
	v_fmac_f32_e32 v69, v70, v70
	v_mul_f32_e32 v93, v93, v93
	v_mul_f32_e32 v81, v81, v81
	v_fmac_f32_e32 v69, v71, v71
	v_fmac_f32_e32 v93, v92, v92
	v_fmac_f32_e32 v81, v80, v80
	v_fmac_f32_e32 v69, v64, v64
	v_fmac_f32_e32 v93, v94, v94
	v_fmac_f32_e32 v81, v82, v82
	v_fmac_f32_e32 v69, v65, v65
	v_mul_f32_e32 v65, v73, v73
	v_fmac_f32_e32 v93, v95, v95
	v_fmac_f32_e32 v81, v83, v83
	v_fmac_f32_e32 v65, v72, v72
	v_fmac_f32_e32 v93, v84, v84
	v_fmac_f32_e32 v81, v76, v76
	v_fmac_f32_e32 v65, v74, v74
	v_fmac_f32_e32 v93, v85, v85
	v_fmac_f32_e32 v81, v77, v77
	v_fmac_f32_e32 v65, v75, v75
	v_fmac_f32_e32 v93, v86, v86
	v_fmac_f32_e32 v81, v78, v78
	v_fmac_f32_e32 v65, v88, v88
	v_fmac_f32_e32 v93, v87, v87
	v_fmac_f32_e32 v81, v79, v79
	v_fmac_f32_e32 v69, v66, v66
	v_fmac_f32_e32 v65, v89, v89
	v_add_f32_e32 v76, v93, v81
	v_fmac_f32_e32 v69, v67, v67
	v_fmac_f32_e32 v65, v90, v90
	v_add_f32_e32 v64, v76, v69
	v_fmac_f32_e32 v65, v91, v91
	v_add_f32_e32 v64, v64, v65
	v_mov_b32_e32 v65, v64
	s_nop 1
	v_permlane16_swap_b32_e32 v64, v65
	v_add_f32_e32 v64, v64, v65
	v_mov_b32_e32 v65, v64
	s_nop 1
	v_permlane32_swap_b32_e32 v64, v65
	global_store_dwordx4 v[102:103], v[96:99], off offset:192
	s_and_saveexec_b64 s[12:13], s[2:3]
	s_cbranch_execz .LBB0_2039
	v_add_f32_e32 v66, v64, v65
	v_lshlrev_b64 v[64:65], 5, v[100:101]
	s_lshl_b32 s34, s30, 1
	s_mov_b32 s35, s9
	v_lshl_add_u64 v[64:65], s[6:7], 0, v[64:65]
	v_lshl_add_u64 v[64:65], s[34:35], 2, v[64:65]
	v_lshl_add_u64 v[64:65], v[134:135], 2, v[64:65]
	global_store_dword v[64:65], v66, off
.LBB0_2039:
	s_or_b64 exec, exec, s[12:13]
	v_cvt_pk_bf16_f32 v68, v60, v61
	v_cvt_pk_bf16_f32 v69, v62, v63
	v_cvt_pk_bf16_f32 v70, v52, v53
	v_cvt_pk_bf16_f32 v71, v54, v55
	v_mov_b32_e32 v64, v68
	v_mov_b32_e32 v66, v70
	v_mov_b32_e32 v65, v69
	v_mov_b32_e32 v67, v71
	v_permlane16_swap_b32_e32 v64, v66
	s_nop 0
	v_permlane16_swap_b32_e32 v65, v67
	s_and_saveexec_b64 s[12:13], vcc
	s_xor_b64 s[12:13], exec, s[12:13]
	v_mov_b32_e32 v67, v71
	v_mov_b32_e32 v66, v70
	s_andn2_saveexec_b64 s[12:13], s[12:13]
	v_mov_b32_e32 v64, v68
	v_mov_b32_e32 v65, v69
	s_or_b64 exec, exec, s[12:13]
	v_or_b32_e32 v68, 32, v138
	v_ashrrev_i32_e32 v69, 31, v68
	v_lshlrev_b64 v[70:71], 11, v[68:69]
	v_lshl_add_u64 v[70:71], s[4:5], 0, v[70:71]
	v_lshl_add_u64 v[70:71], s[8:9], 1, v[70:71]
	v_lshl_add_u64 v[70:71], v[136:137], 1, v[70:71]
	v_cvt_pk_bf16_f32 v72, v48, v49
	v_cvt_pk_bf16_f32 v73, v50, v51
	v_cvt_pk_bf16_f32 v74, v40, v41
	v_cvt_pk_bf16_f32 v75, v42, v43
	global_store_dwordx4 v[70:71], v[64:67], off
	s_nop 1
	v_mov_b32_e32 v66, v74
	v_mov_b32_e32 v64, v72
	v_mov_b32_e32 v67, v75
	v_mov_b32_e32 v65, v73
	v_permlane16_swap_b32_e32 v64, v66
	s_nop 0
	v_permlane16_swap_b32_e32 v65, v67
	s_and_saveexec_b64 s[12:13], vcc
	s_xor_b64 s[12:13], exec, s[12:13]
	v_mov_b32_e32 v67, v75
	v_mov_b32_e32 v66, v74
	s_andn2_saveexec_b64 s[12:13], s[12:13]
	v_mov_b32_e32 v64, v72
	v_mov_b32_e32 v65, v73
	s_or_b64 exec, exec, s[12:13]
	v_cvt_pk_bf16_f32 v72, v36, v37
	v_cvt_pk_bf16_f32 v73, v38, v39
	v_cvt_pk_bf16_f32 v74, v32, v33
	v_cvt_pk_bf16_f32 v75, v34, v35
	global_store_dwordx4 v[70:71], v[64:67], off offset:64
	s_nop 1
	v_mov_b32_e32 v66, v74
	v_mov_b32_e32 v64, v72
	v_mov_b32_e32 v67, v75
	v_mov_b32_e32 v65, v73
	v_permlane16_swap_b32_e32 v64, v66
	s_nop 0
	v_permlane16_swap_b32_e32 v65, v67
	s_and_saveexec_b64 s[12:13], vcc
	s_xor_b64 s[12:13], exec, s[12:13]
	v_mov_b32_e32 v67, v75
	v_mov_b32_e32 v66, v74
	s_andn2_saveexec_b64 s[12:13], s[12:13]
	v_mov_b32_e32 v64, v72
	v_mov_b32_e32 v65, v73
	s_or_b64 exec, exec, s[12:13]
	v_cvt_pk_bf16_f32 v72, v44, v45
	v_cvt_pk_bf16_f32 v73, v46, v47
	v_cvt_pk_bf16_f32 v74, v56, v57
	v_cvt_pk_bf16_f32 v75, v58, v59
	global_store_dwordx4 v[70:71], v[64:67], off offset:128
	s_nop 1
	v_mov_b32_e32 v66, v74
	v_mov_b32_e32 v64, v72
	v_mov_b32_e32 v67, v75
	v_mov_b32_e32 v65, v73
	v_permlane16_swap_b32_e32 v64, v66
	s_nop 0
	v_permlane16_swap_b32_e32 v65, v67
	s_and_saveexec_b64 s[12:13], vcc
	s_xor_b64 s[12:13], exec, s[12:13]
	v_mov_b32_e32 v67, v75
	v_mov_b32_e32 v66, v74
	s_andn2_saveexec_b64 s[12:13], s[12:13]
	v_mov_b32_e32 v64, v72
	v_mov_b32_e32 v65, v73
	s_or_b64 exec, exec, s[12:13]
	v_mul_f32_e32 v37, v37, v37
	v_fmac_f32_e32 v37, v36, v36
	v_fmac_f32_e32 v37, v38, v38
	v_mul_f32_e32 v61, v61, v61
	v_mul_f32_e32 v49, v49, v49
	v_fmac_f32_e32 v37, v39, v39
	v_fmac_f32_e32 v61, v60, v60
	v_fmac_f32_e32 v49, v48, v48
	v_fmac_f32_e32 v37, v32, v32
	v_fmac_f32_e32 v61, v62, v62
	v_fmac_f32_e32 v49, v50, v50
	v_fmac_f32_e32 v37, v33, v33
	v_mul_f32_e32 v33, v45, v45
	v_fmac_f32_e32 v61, v63, v63
	v_fmac_f32_e32 v49, v51, v51
	v_fmac_f32_e32 v33, v44, v44
	v_fmac_f32_e32 v61, v52, v52
	v_fmac_f32_e32 v49, v40, v40
	v_fmac_f32_e32 v33, v46, v46
	v_fmac_f32_e32 v61, v53, v53
	v_fmac_f32_e32 v49, v41, v41
	v_fmac_f32_e32 v33, v47, v47
	v_fmac_f32_e32 v61, v54, v54
	v_fmac_f32_e32 v49, v42, v42
	v_fmac_f32_e32 v33, v56, v56
	v_fmac_f32_e32 v61, v55, v55
	v_fmac_f32_e32 v49, v43, v43
	v_fmac_f32_e32 v37, v34, v34
	v_fmac_f32_e32 v33, v57, v57
	v_add_f32_e32 v40, v61, v49
	v_fmac_f32_e32 v37, v35, v35
	v_fmac_f32_e32 v33, v58, v58
	v_add_f32_e32 v32, v40, v37
	v_fmac_f32_e32 v33, v59, v59
	v_add_f32_e32 v32, v32, v33
	v_mov_b32_e32 v33, v32
	s_nop 1
	v_permlane16_swap_b32_e32 v32, v33
	v_add_f32_e32 v32, v32, v33
	v_mov_b32_e32 v33, v32
	s_nop 1
	v_permlane32_swap_b32_e32 v32, v33
	global_store_dwordx4 v[70:71], v[64:67], off offset:192
	s_and_saveexec_b64 s[12:13], s[2:3]
	s_cbranch_execz .LBB0_2057
	v_add_f32_e32 v34, v32, v33
	v_lshlrev_b64 v[32:33], 5, v[68:69]
	s_lshl_b32 s34, s30, 1
	s_mov_b32 s35, s9
	v_lshl_add_u64 v[32:33], s[6:7], 0, v[32:33]
	v_lshl_add_u64 v[32:33], s[34:35], 2, v[32:33]
	v_lshl_add_u64 v[32:33], v[134:135], 2, v[32:33]
	global_store_dword v[32:33], v34, off
.LBB0_2057:
	s_or_b64 exec, exec, s[12:13]
	v_cvt_pk_bf16_f32 v36, v24, v25
	v_cvt_pk_bf16_f32 v37, v26, v27
	v_cvt_pk_bf16_f32 v38, v20, v21
	v_cvt_pk_bf16_f32 v39, v22, v23
	v_mov_b32_e32 v32, v36
	v_mov_b32_e32 v34, v38
	v_mov_b32_e32 v35, v39
	v_mov_b32_e32 v33, v37
	v_permlane16_swap_b32_e32 v32, v34
	s_nop 0
	v_permlane16_swap_b32_e32 v33, v35
	s_and_saveexec_b64 s[12:13], vcc
	s_xor_b64 s[12:13], exec, s[12:13]
	v_mov_b32_e32 v35, v39
	v_mov_b32_e32 v34, v38
	s_andn2_saveexec_b64 s[12:13], s[12:13]
	v_mov_b32_e32 v32, v36
	v_mov_b32_e32 v33, v37
	s_or_b64 exec, exec, s[12:13]
	v_or_b32_e32 v36, 48, v138
	v_ashrrev_i32_e32 v37, 31, v36
	v_lshlrev_b64 v[38:39], 11, v[36:37]
	v_lshl_add_u64 v[38:39], s[4:5], 0, v[38:39]
	v_lshl_add_u64 v[38:39], s[8:9], 1, v[38:39]
	v_lshl_add_u64 v[38:39], v[136:137], 1, v[38:39]
	v_cvt_pk_bf16_f32 v40, v12, v13
	v_cvt_pk_bf16_f32 v41, v14, v15
	v_cvt_pk_bf16_f32 v42, v8, v9
	v_cvt_pk_bf16_f32 v43, v10, v11
	global_store_dwordx4 v[38:39], v[32:35], off
	s_nop 1
	v_mov_b32_e32 v34, v42
	v_mov_b32_e32 v32, v40
	v_mov_b32_e32 v33, v41
	v_mov_b32_e32 v35, v43
	v_permlane16_swap_b32_e32 v32, v34
	s_nop 0
	v_permlane16_swap_b32_e32 v33, v35
	s_and_saveexec_b64 s[12:13], vcc
	s_xor_b64 s[12:13], exec, s[12:13]
	v_mov_b32_e32 v35, v43
	v_mov_b32_e32 v34, v42
	s_andn2_saveexec_b64 s[12:13], s[12:13]
	v_mov_b32_e32 v32, v40
	v_mov_b32_e32 v33, v41
	s_or_b64 exec, exec, s[12:13]
	v_cvt_pk_bf16_f32 v40, v4, v5
	v_cvt_pk_bf16_f32 v41, v6, v7
	v_cvt_pk_bf16_f32 v42, v0, v1
	v_cvt_pk_bf16_f32 v43, v2, v3
	global_store_dwordx4 v[38:39], v[32:35], off offset:64
	s_nop 1
	v_mov_b32_e32 v34, v42
	v_mov_b32_e32 v32, v40
	v_mov_b32_e32 v33, v41
	v_mov_b32_e32 v35, v43
	v_permlane16_swap_b32_e32 v32, v34
	s_nop 0
	v_permlane16_swap_b32_e32 v33, v35
	s_and_saveexec_b64 s[12:13], vcc
	s_xor_b64 s[12:13], exec, s[12:13]
	v_mov_b32_e32 v35, v43
	v_mov_b32_e32 v34, v42
	s_andn2_saveexec_b64 s[12:13], s[12:13]
	v_mov_b32_e32 v32, v40
	v_mov_b32_e32 v33, v41
	s_or_b64 exec, exec, s[12:13]
	v_cvt_pk_bf16_f32 v40, v16, v17
	v_cvt_pk_bf16_f32 v41, v18, v19
	v_cvt_pk_bf16_f32 v42, v28, v29
	v_cvt_pk_bf16_f32 v43, v30, v31
	global_store_dwordx4 v[38:39], v[32:35], off offset:128
	s_nop 1
	v_mov_b32_e32 v34, v42
	v_mov_b32_e32 v32, v40
	v_mov_b32_e32 v33, v41
	v_mov_b32_e32 v35, v43
	v_permlane16_swap_b32_e32 v32, v34
	s_nop 0
	v_permlane16_swap_b32_e32 v33, v35
	s_and_saveexec_b64 s[12:13], vcc
	s_xor_b64 s[12:13], exec, s[12:13]
	v_mov_b32_e32 v35, v43
	v_mov_b32_e32 v34, v42
	s_andn2_saveexec_b64 s[12:13], s[12:13]
	v_mov_b32_e32 v32, v40
	v_mov_b32_e32 v33, v41
	s_or_b64 exec, exec, s[12:13]
	v_mul_f32_e32 v5, v5, v5
	v_fmac_f32_e32 v5, v4, v4
	v_fmac_f32_e32 v5, v6, v6
	v_mul_f32_e32 v25, v25, v25
	v_mul_f32_e32 v13, v13, v13
	v_fmac_f32_e32 v5, v7, v7
	v_fmac_f32_e32 v25, v24, v24
	v_fmac_f32_e32 v13, v12, v12
	v_fmac_f32_e32 v5, v0, v0
	v_fmac_f32_e32 v25, v26, v26
	v_fmac_f32_e32 v13, v14, v14
	v_fmac_f32_e32 v5, v1, v1
	v_mul_f32_e32 v1, v17, v17
	v_fmac_f32_e32 v25, v27, v27
	v_fmac_f32_e32 v13, v15, v15
	v_fmac_f32_e32 v1, v16, v16
	v_fmac_f32_e32 v25, v20, v20
	v_fmac_f32_e32 v13, v8, v8
	v_fmac_f32_e32 v1, v18, v18
	v_fmac_f32_e32 v25, v21, v21
	v_fmac_f32_e32 v13, v9, v9
	v_fmac_f32_e32 v1, v19, v19
	v_fmac_f32_e32 v25, v22, v22
	v_fmac_f32_e32 v13, v10, v10
	v_fmac_f32_e32 v1, v28, v28
	v_fmac_f32_e32 v25, v23, v23
	v_fmac_f32_e32 v13, v11, v11
	v_fmac_f32_e32 v5, v2, v2
	v_fmac_f32_e32 v1, v29, v29
	v_add_f32_e32 v8, v25, v13
	v_fmac_f32_e32 v5, v3, v3
	v_fmac_f32_e32 v1, v30, v30
	v_add_f32_e32 v0, v8, v5
	v_fmac_f32_e32 v1, v31, v31
	v_add_f32_e32 v0, v0, v1
	v_mov_b32_e32 v1, v0
	s_nop 1
	v_permlane16_swap_b32_e32 v0, v1
	v_add_f32_e32 v0, v0, v1
	v_mov_b32_e32 v1, v0
	s_nop 1
	v_permlane32_swap_b32_e32 v0, v1
	global_store_dwordx4 v[38:39], v[32:35], off offset:192
	s_and_saveexec_b64 s[12:13], s[2:3]
	s_xor_b64 s[2:3], exec, s[12:13]
	s_cbranch_execz .LBB0_1992
	v_add_f32_e32 v2, v0, v1
	v_lshlrev_b64 v[0:1], 5, v[36:37]
	s_lshl_b32 s8, s30, 1
	v_lshl_add_u64 v[0:1], s[6:7], 0, v[0:1]
	v_lshl_add_u64 v[0:1], s[8:9], 2, v[0:1]
	v_lshl_add_u64 v[0:1], v[134:135], 2, v[0:1]
	global_store_dword v[0:1], v2, off
	s_branch .LBB0_1992

.LBB0_2122:
	v_and_b32_e32 v128, 16, v139
	v_cvt_pk_bf16_f32 v134, v124, v125
	v_cvt_pk_bf16_f32 v141, v126, v127
	v_cvt_pk_bf16_f32 v142, v120, v121
	v_cvt_pk_bf16_f32 v143, v122, v123
	v_cmp_eq_u32_e32 vcc, 0, v128
	v_cmp_ne_u32_e64 s[4:5], 0, v128
	v_mov_b32_e32 v130, v142
	v_mov_b32_e32 v128, v134
	v_mov_b32_e32 v131, v143
	v_mov_b32_e32 v129, v141
	v_permlane16_swap_b32_e32 v128, v130
	s_nop 0
	v_permlane16_swap_b32_e32 v129, v131
	s_and_saveexec_b64 s[6:7], s[4:5]
	s_xor_b64 s[6:7], exec, s[6:7]
	v_mov_b32_e32 v131, v143
	v_mov_b32_e32 v130, v142
	s_andn2_saveexec_b64 s[6:7], s[6:7]
	v_mov_b32_e32 v128, v134
	v_mov_b32_e32 v129, v141
	s_or_b64 exec, exec, s[6:7]
	v_and_b32_e32 v139, 0xcf, v139
	v_lshl_or_b32 v144, s18, 8, v139
	v_add_u32_e32 v134, 12, v138
	v_ashrrev_i32_e32 v145, 31, v144
	v_cndmask_b32_e32 v134, v134, v138, vcc
	v_lshlrev_b64 v[146:147], 11, v[144:145]
	v_or_b32_e32 v142, v134, v140
	v_lshl_add_u64 v[146:147], s[14:15], 0, v[146:147]
	v_lshl_add_u64 v[148:149], s[20:21], 1, v[146:147]
	v_ashrrev_i32_e32 v143, 31, v142
	v_lshl_add_u64 v[146:147], v[142:143], 1, v[148:149]
	s_and_b64 vcc, exec, s[2:3]
	v_ashrrev_i32_e32 v141, 31, v140
	global_store_dwordx4 v[146:147], v[128:131], off
	s_cbranch_vccnz .LBB0_2128
	v_mov_b32_e32 v139, v135
	v_lshl_add_u64 v[128:129], v[140:141], 0, v[138:139]
	v_lshl_add_u64 v[128:129], v[128:129], 0, s[20:21]
	v_lshlrev_b64 v[146:147], 2, v[128:129]
	v_lshl_add_u64 v[128:129], s[8:9], 0, v[146:147]
	v_pk_add_f32 v[118:119], v[118:119], v[208:209]
	v_pk_add_f32 v[116:117], v[116:117], v[206:207]
	v_pk_mul_f32 v[118:119], v[118:119], v[240:241]
	v_pk_mul_f32 v[116:117], v[116:117], v[238:239]

.LBB0_2130:
	v_cvt_pk_bf16_f32 v139, v116, v117
	v_cvt_pk_bf16_f32 v150, v118, v119
	v_cvt_pk_bf16_f32 v151, v112, v113
	v_cvt_pk_bf16_f32 v152, v114, v115
	v_mov_b32_e32 v130, v151
	v_mov_b32_e32 v128, v139
	v_mov_b32_e32 v129, v150
	v_mov_b32_e32 v131, v152
	v_permlane16_swap_b32_e32 v128, v130
	s_nop 0
	v_permlane16_swap_b32_e32 v129, v131
	s_and_saveexec_b64 s[6:7], s[4:5]
	s_xor_b64 s[6:7], exec, s[6:7]
	v_mov_b32_e32 v131, v152
	v_mov_b32_e32 v130, v151
	s_andn2_saveexec_b64 s[6:7], s[6:7]
	v_mov_b32_e32 v128, v139
	v_mov_b32_e32 v129, v150
	s_or_b64 exec, exec, s[6:7]
	v_lshl_add_u64 v[152:153], v[134:135], 0, v[140:141]
	v_lshl_add_u64 v[154:155], v[152:153], 1, v[148:149]
	s_and_b64 vcc, exec, s[2:3]
	global_store_dwordx4 v[154:155], v[128:131], off offset:64
	s_cbranch_vccnz .LBB0_2136
	v_mov_b32_e32 v139, v135
	v_lshl_add_u64 v[128:129], v[140:141], 0, v[138:139]
	v_lshl_add_u64 v[128:129], v[128:129], 0, s[20:21]
	v_lshlrev_b64 v[148:149], 2, v[128:129]
	v_lshl_add_u64 v[128:129], s[8:9], 0, v[148:149]
	v_pk_add_f32 v[110:111], v[110:111], v[216:217]
	v_pk_add_f32 v[108:109], v[108:109], v[214:215]
	v_pk_mul_f32 v[110:111], v[110:111], v[248:249]
	v_pk_mul_f32 v[108:109], v[108:109], v[246:247]

.LBB0_2140:
	s_or_b64 exec, exec, s[6:7]
	s_and_b64 vcc, exec, s[2:3]
	global_store_dwordx4 v[154:155], v[128:131], off offset:128
	s_cbranch_vccnz .LBB0_2142

.LBB0_2144:
	v_cvt_pk_bf16_f32 v134, v96, v97
	v_cvt_pk_bf16_f32 v139, v98, v99
	v_cvt_pk_bf16_f32 v157, v104, v105
	v_cvt_pk_bf16_f32 v158, v106, v107
	v_mov_b32_e32 v128, v134
	v_mov_b32_e32 v130, v157
	v_mov_b32_e32 v129, v139
	v_mov_b32_e32 v131, v158
	v_permlane16_swap_b32_e32 v128, v130
	s_nop 0
	v_permlane16_swap_b32_e32 v129, v131
	s_and_saveexec_b64 s[6:7], s[4:5]
	s_xor_b64 s[6:7], exec, s[6:7]
	v_mov_b32_e32 v131, v158
	v_mov_b32_e32 v130, v157
	s_andn2_saveexec_b64 s[6:7], s[6:7]
	v_mov_b32_e32 v128, v134
	v_mov_b32_e32 v129, v139
	s_or_b64 exec, exec, s[6:7]
	v_mul_f32_e32 v125, v125, v125
	v_mul_f32_e32 v117, v117, v117
	v_fmac_f32_e32 v125, v124, v124
	v_fmac_f32_e32 v117, v116, v116
	v_mul_f32_e32 v109, v109, v109
	v_fmac_f32_e32 v125, v126, v126
	v_fmac_f32_e32 v117, v118, v118
	v_fmac_f32_e32 v109, v108, v108
	v_mul_f32_e32 v97, v97, v97
	v_fmac_f32_e32 v125, v127, v127
	v_fmac_f32_e32 v117, v119, v119
	v_fmac_f32_e32 v109, v110, v110
	v_fmac_f32_e32 v97, v96, v96
	v_fmac_f32_e32 v125, v120, v120
	v_fmac_f32_e32 v117, v112, v112
	v_fmac_f32_e32 v109, v111, v111
	v_fmac_f32_e32 v97, v98, v98
	v_fmac_f32_e32 v125, v121, v121
	v_fmac_f32_e32 v117, v113, v113
	v_fmac_f32_e32 v109, v100, v100
	v_fmac_f32_e32 v97, v99, v99
	v_fmac_f32_e32 v125, v122, v122
	v_fmac_f32_e32 v117, v114, v114
	v_fmac_f32_e32 v109, v101, v101
	v_fmac_f32_e32 v97, v104, v104
	v_fmac_f32_e32 v125, v123, v123
	v_fmac_f32_e32 v117, v115, v115
	v_fmac_f32_e32 v109, v102, v102
	v_fmac_f32_e32 v97, v105, v105
	v_add_f32_e32 v112, v125, v117
	v_fmac_f32_e32 v109, v103, v103
	v_fmac_f32_e32 v97, v106, v106
	v_add_f32_e32 v100, v112, v109
	v_fmac_f32_e32 v97, v107, v107
	v_add_f32_e32 v96, v100, v97
	v_mov_b32_e32 v97, v96
	s_nop 1
	v_permlane16_swap_b32_e32 v96, v97
	v_add_f32_e32 v96, v96, v97
	v_mov_b32_e32 v97, v96
	v_cmp_eq_u32_e64 s[6:7], 0, v137
	v_ashrrev_i32_e32 v137, 31, v136
	v_permlane32_swap_b32_e32 v96, v97
	global_store_dwordx4 v[154:155], v[128:131], off offset:192
	s_and_saveexec_b64 s[22:23], s[6:7]
	s_cbranch_execz .LBB0_2150
	s_lshl_b32 s19, s18, 3
	v_add_f32_e32 v98, v96, v97
	s_sub_i32 s90, s24, s19
	v_lshlrev_b64 v[96:97], 5, v[144:145]
	s_ashr_i32 s91, s90, 31
	v_lshl_add_u64 v[96:97], s[12:13], 0, v[96:97]
	v_lshl_add_u64 v[96:97], s[90:91], 2, v[96:97]
	v_lshl_add_u64 v[96:97], v[136:137], 2, v[96:97]
	global_store_dword v[96:97], v98, off

.LBB0_2154:
	v_cvt_pk_bf16_f32 v100, v92, v93
	v_cvt_pk_bf16_f32 v101, v94, v95
	v_cvt_pk_bf16_f32 v102, v88, v89
	v_cvt_pk_bf16_f32 v103, v90, v91
	v_mov_b32_e32 v96, v100
	v_mov_b32_e32 v98, v102
	v_mov_b32_e32 v99, v103
	v_mov_b32_e32 v97, v101
	v_permlane16_swap_b32_e32 v96, v98
	s_nop 0
	v_permlane16_swap_b32_e32 v97, v99
	s_and_saveexec_b64 s[22:23], s[4:5]
	s_xor_b64 s[22:23], exec, s[22:23]
	v_mov_b32_e32 v99, v103
	v_mov_b32_e32 v98, v102
	s_andn2_saveexec_b64 s[22:23], s[22:23]
	v_mov_b32_e32 v96, v100
	v_mov_b32_e32 v97, v101
	s_or_b64 exec, exec, s[22:23]
	v_or_b32_e32 v100, 16, v144
	v_ashrrev_i32_e32 v101, 31, v100
	v_lshlrev_b64 v[102:103], 11, v[100:101]
	v_lshl_add_u64 v[102:103], s[14:15], 0, v[102:103]
	v_lshl_add_u64 v[102:103], s[20:21], 1, v[102:103]
	v_lshl_add_u64 v[104:105], v[142:143], 1, v[102:103]
	s_and_b64 vcc, exec, s[2:3]
	global_store_dwordx4 v[104:105], v[96:99], off
	s_cbranch_vccnz .LBB0_2160
	v_mov_b32_e32 v139, v135
	v_lshl_add_u64 v[96:97], v[140:141], 0, v[138:139]
	v_lshl_add_u64 v[96:97], v[96:97], 0, s[20:21]
	v_lshlrev_b64 v[104:105], 2, v[96:97]
	v_lshl_add_u64 v[96:97], s[8:9], 0, v[104:105]
	v_pk_add_f32 v[86:87], v[86:87], v[208:209]
	v_pk_add_f32 v[84:85], v[84:85], v[206:207]
	v_pk_mul_f32 v[86:87], v[86:87], v[240:241]
	v_pk_mul_f32 v[84:85], v[84:85], v[238:239]

.LBB0_2162:
	v_cvt_pk_bf16_f32 v104, v84, v85
	v_cvt_pk_bf16_f32 v105, v86, v87
	v_cvt_pk_bf16_f32 v106, v80, v81
	v_cvt_pk_bf16_f32 v107, v82, v83
	v_mov_b32_e32 v98, v106
	v_mov_b32_e32 v96, v104
	v_mov_b32_e32 v97, v105
	v_mov_b32_e32 v99, v107
	v_permlane16_swap_b32_e32 v96, v98
	s_nop 0
	v_permlane16_swap_b32_e32 v97, v99
	s_and_saveexec_b64 s[22:23], s[4:5]
	s_xor_b64 s[22:23], exec, s[22:23]
	v_mov_b32_e32 v99, v107
	v_mov_b32_e32 v98, v106
	s_andn2_saveexec_b64 s[22:23], s[22:23]
	v_mov_b32_e32 v96, v104
	v_mov_b32_e32 v97, v105
	s_or_b64 exec, exec, s[22:23]
	v_lshl_add_u64 v[102:103], v[152:153], 1, v[102:103]
	s_and_b64 vcc, exec, s[2:3]
	global_store_dwordx4 v[102:103], v[96:99], off offset:64
	s_cbranch_vccnz .LBB0_2168
	v_mov_b32_e32 v139, v135
	v_lshl_add_u64 v[96:97], v[140:141], 0, v[138:139]
	v_lshl_add_u64 v[96:97], v[96:97], 0, s[20:21]
	v_lshlrev_b64 v[104:105], 2, v[96:97]
	v_lshl_add_u64 v[96:97], s[8:9], 0, v[104:105]
	v_pk_add_f32 v[74:75], v[74:75], v[216:217]
	v_pk_add_f32 v[72:73], v[72:73], v[214:215]
	v_pk_mul_f32 v[74:75], v[74:75], v[248:249]
	v_pk_mul_f32 v[72:73], v[72:73], v[246:247]

.LBB0_2172:
	s_or_b64 exec, exec, s[22:23]
	s_and_b64 vcc, exec, s[2:3]
	global_store_dwordx4 v[102:103], v[96:99], off offset:128
	s_cbranch_vccnz .LBB0_2174

.LBB0_2176:
	v_cvt_pk_bf16_f32 v104, v64, v65
	v_cvt_pk_bf16_f32 v105, v66, v67
	v_cvt_pk_bf16_f32 v106, v76, v77
	v_cvt_pk_bf16_f32 v107, v78, v79
	v_mov_b32_e32 v96, v104
	v_mov_b32_e32 v98, v106
	v_mov_b32_e32 v97, v105
	v_mov_b32_e32 v99, v107
	v_permlane16_swap_b32_e32 v96, v98
	s_nop 0
	v_permlane16_swap_b32_e32 v97, v99
	s_and_saveexec_b64 s[22:23], s[4:5]
	s_xor_b64 s[22:23], exec, s[22:23]
	v_mov_b32_e32 v99, v107
	v_mov_b32_e32 v98, v106
	s_andn2_saveexec_b64 s[22:23], s[22:23]
	v_mov_b32_e32 v96, v104
	v_mov_b32_e32 v97, v105
	s_or_b64 exec, exec, s[22:23]
	v_mul_f32_e32 v93, v93, v93
	v_mul_f32_e32 v85, v85, v85
	v_fmac_f32_e32 v93, v92, v92
	v_fmac_f32_e32 v85, v84, v84
	v_mul_f32_e32 v73, v73, v73
	v_fmac_f32_e32 v93, v94, v94
	v_fmac_f32_e32 v85, v86, v86
	v_fmac_f32_e32 v73, v72, v72
	v_mul_f32_e32 v65, v65, v65
	v_fmac_f32_e32 v93, v95, v95
	v_fmac_f32_e32 v85, v87, v87
	v_fmac_f32_e32 v73, v74, v74
	v_fmac_f32_e32 v65, v64, v64
	v_fmac_f32_e32 v93, v88, v88
	v_fmac_f32_e32 v85, v80, v80
	v_fmac_f32_e32 v73, v75, v75
	v_fmac_f32_e32 v65, v66, v66
	v_fmac_f32_e32 v93, v89, v89
	v_fmac_f32_e32 v85, v81, v81
	v_fmac_f32_e32 v73, v68, v68
	v_fmac_f32_e32 v65, v67, v67
	v_fmac_f32_e32 v93, v90, v90
	v_fmac_f32_e32 v85, v82, v82
	v_fmac_f32_e32 v73, v69, v69
	v_fmac_f32_e32 v65, v76, v76
	v_fmac_f32_e32 v93, v91, v91
	v_fmac_f32_e32 v85, v83, v83
	v_fmac_f32_e32 v73, v70, v70
	v_fmac_f32_e32 v65, v77, v77
	v_add_f32_e32 v80, v93, v85
	v_fmac_f32_e32 v73, v71, v71
	v_fmac_f32_e32 v65, v78, v78
	v_add_f32_e32 v68, v80, v73
	v_fmac_f32_e32 v65, v79, v79
	v_add_f32_e32 v64, v68, v65
	v_mov_b32_e32 v65, v64
	s_nop 1
	v_permlane16_swap_b32_e32 v64, v65
	v_add_f32_e32 v64, v64, v65
	v_mov_b32_e32 v65, v64
	s_nop 1
	v_permlane32_swap_b32_e32 v64, v65
	global_store_dwordx4 v[102:103], v[96:99], off offset:192
	s_and_saveexec_b64 s[22:23], s[6:7]
	s_cbranch_execz .LBB0_2182
	s_lshl_b32 s19, s18, 3
	v_add_f32_e32 v66, v64, v65
	s_sub_i32 s90, s24, s19
	v_lshlrev_b64 v[64:65], 5, v[100:101]
	s_ashr_i32 s91, s90, 31
	v_lshl_add_u64 v[64:65], s[12:13], 0, v[64:65]
	v_lshl_add_u64 v[64:65], s[90:91], 2, v[64:65]
	v_lshl_add_u64 v[64:65], v[136:137], 2, v[64:65]
	global_store_dword v[64:65], v66, off

.LBB0_2186:
	v_cvt_pk_bf16_f32 v68, v60, v61
	v_cvt_pk_bf16_f32 v69, v62, v63
	v_cvt_pk_bf16_f32 v70, v56, v57
	v_cvt_pk_bf16_f32 v71, v58, v59
	v_mov_b32_e32 v66, v70
	v_mov_b32_e32 v64, v68
	v_mov_b32_e32 v65, v69
	v_mov_b32_e32 v67, v71
	v_permlane16_swap_b32_e32 v64, v66
	s_nop 0
	v_permlane16_swap_b32_e32 v65, v67
	s_and_saveexec_b64 s[22:23], s[4:5]
	s_xor_b64 s[22:23], exec, s[22:23]
	v_mov_b32_e32 v67, v71
	v_mov_b32_e32 v66, v70
	s_andn2_saveexec_b64 s[22:23], s[22:23]
	v_mov_b32_e32 v64, v68
	v_mov_b32_e32 v65, v69
	s_or_b64 exec, exec, s[22:23]
	v_or_b32_e32 v68, 32, v144
	v_ashrrev_i32_e32 v69, 31, v68
	v_lshlrev_b64 v[70:71], 11, v[68:69]
	v_lshl_add_u64 v[70:71], s[14:15], 0, v[70:71]
	v_lshl_add_u64 v[70:71], s[20:21], 1, v[70:71]
	v_lshl_add_u64 v[72:73], v[142:143], 1, v[70:71]
	s_and_b64 vcc, exec, s[2:3]
	global_store_dwordx4 v[72:73], v[64:67], off
	s_cbranch_vccnz .LBB0_2192
	v_mov_b32_e32 v139, v135
	v_lshl_add_u64 v[64:65], v[140:141], 0, v[138:139]
	v_lshl_add_u64 v[64:65], v[64:65], 0, s[20:21]
	v_lshlrev_b64 v[72:73], 2, v[64:65]
	v_lshl_add_u64 v[64:65], s[8:9], 0, v[72:73]
	v_pk_add_f32 v[54:55], v[54:55], v[208:209]
	v_pk_add_f32 v[52:53], v[52:53], v[206:207]
	v_pk_mul_f32 v[54:55], v[54:55], v[240:241]
	v_pk_mul_f32 v[52:53], v[52:53], v[238:239]

.LBB0_2194:
	v_cvt_pk_bf16_f32 v72, v52, v53
	v_cvt_pk_bf16_f32 v73, v54, v55
	v_cvt_pk_bf16_f32 v74, v44, v45
	v_cvt_pk_bf16_f32 v75, v46, v47
	v_mov_b32_e32 v64, v72
	v_mov_b32_e32 v66, v74
	v_mov_b32_e32 v67, v75
	v_mov_b32_e32 v65, v73
	v_permlane16_swap_b32_e32 v64, v66
	s_nop 0
	v_permlane16_swap_b32_e32 v65, v67
	s_and_saveexec_b64 s[22:23], s[4:5]
	s_xor_b64 s[22:23], exec, s[22:23]
	v_mov_b32_e32 v67, v75
	v_mov_b32_e32 v66, v74
	s_andn2_saveexec_b64 s[22:23], s[22:23]
	v_mov_b32_e32 v64, v72
	v_mov_b32_e32 v65, v73
	s_or_b64 exec, exec, s[22:23]
	v_lshl_add_u64 v[70:71], v[152:153], 1, v[70:71]
	s_and_b64 vcc, exec, s[2:3]
	global_store_dwordx4 v[70:71], v[64:67], off offset:64
	s_cbranch_vccnz .LBB0_2200
	v_mov_b32_e32 v139, v135
	v_lshl_add_u64 v[64:65], v[140:141], 0, v[138:139]
	v_lshl_add_u64 v[64:65], v[64:65], 0, s[20:21]
	v_lshlrev_b64 v[72:73], 2, v[64:65]
	v_lshl_add_u64 v[64:65], s[8:9], 0, v[72:73]
	v_pk_add_f32 v[42:43], v[42:43], v[216:217]
	v_pk_add_f32 v[40:41], v[40:41], v[214:215]
	v_pk_mul_f32 v[42:43], v[42:43], v[248:249]
	v_pk_mul_f32 v[40:41], v[40:41], v[246:247]

.LBB0_2204:
	s_or_b64 exec, exec, s[22:23]
	s_and_b64 vcc, exec, s[2:3]
	global_store_dwordx4 v[70:71], v[64:67], off offset:128
	s_cbranch_vccnz .LBB0_2206

.LBB0_2208:
	v_cvt_pk_bf16_f32 v72, v32, v33
	v_cvt_pk_bf16_f32 v73, v34, v35
	v_cvt_pk_bf16_f32 v74, v48, v49
	v_cvt_pk_bf16_f32 v75, v50, v51
	v_mov_b32_e32 v66, v74
	v_mov_b32_e32 v64, v72
	v_mov_b32_e32 v67, v75
	v_mov_b32_e32 v65, v73
	v_permlane16_swap_b32_e32 v64, v66
	s_nop 0
	v_permlane16_swap_b32_e32 v65, v67
	s_and_saveexec_b64 s[22:23], s[4:5]
	s_xor_b64 s[22:23], exec, s[22:23]
	v_mov_b32_e32 v67, v75
	v_mov_b32_e32 v66, v74
	s_andn2_saveexec_b64 s[22:23], s[22:23]
	v_mov_b32_e32 v64, v72
	v_mov_b32_e32 v65, v73
	s_or_b64 exec, exec, s[22:23]
	v_mul_f32_e32 v61, v61, v61
	v_mul_f32_e32 v53, v53, v53
	v_fmac_f32_e32 v61, v60, v60
	v_fmac_f32_e32 v53, v52, v52
	v_mul_f32_e32 v41, v41, v41
	v_fmac_f32_e32 v61, v62, v62
	v_fmac_f32_e32 v53, v54, v54
	v_fmac_f32_e32 v41, v40, v40
	v_mul_f32_e32 v33, v33, v33
	v_fmac_f32_e32 v61, v63, v63
	v_fmac_f32_e32 v53, v55, v55
	v_fmac_f32_e32 v41, v42, v42
	v_fmac_f32_e32 v33, v32, v32
	v_fmac_f32_e32 v61, v56, v56
	v_fmac_f32_e32 v53, v44, v44
	v_fmac_f32_e32 v41, v43, v43
	v_fmac_f32_e32 v33, v34, v34
	v_fmac_f32_e32 v61, v57, v57
	v_fmac_f32_e32 v53, v45, v45
	v_fmac_f32_e32 v41, v36, v36
	v_fmac_f32_e32 v33, v35, v35
	v_fmac_f32_e32 v61, v58, v58
	v_fmac_f32_e32 v53, v46, v46
	v_fmac_f32_e32 v41, v37, v37
	v_fmac_f32_e32 v33, v48, v48
	v_fmac_f32_e32 v61, v59, v59
	v_fmac_f32_e32 v53, v47, v47
	v_fmac_f32_e32 v41, v38, v38
	v_fmac_f32_e32 v33, v49, v49
	v_add_f32_e32 v44, v61, v53
	v_fmac_f32_e32 v41, v39, v39
	v_fmac_f32_e32 v33, v50, v50
	v_add_f32_e32 v36, v44, v41
	v_fmac_f32_e32 v33, v51, v51
	v_add_f32_e32 v32, v36, v33
	v_mov_b32_e32 v33, v32
	s_nop 1
	v_permlane16_swap_b32_e32 v32, v33
	v_add_f32_e32 v32, v32, v33
	v_mov_b32_e32 v33, v32
	s_nop 1
	v_permlane32_swap_b32_e32 v32, v33
	global_store_dwordx4 v[70:71], v[64:67], off offset:192
	s_and_saveexec_b64 s[22:23], s[6:7]
	s_cbranch_execz .LBB0_2214
	s_lshl_b32 s19, s18, 3
	v_add_f32_e32 v34, v32, v33
	s_sub_i32 s90, s24, s19
	v_lshlrev_b64 v[32:33], 5, v[68:69]
	s_ashr_i32 s91, s90, 31
	v_lshl_add_u64 v[32:33], s[12:13], 0, v[32:33]
	v_lshl_add_u64 v[32:33], s[90:91], 2, v[32:33]
	v_lshl_add_u64 v[32:33], v[136:137], 2, v[32:33]
	global_store_dword v[32:33], v34, off

.LBB0_2218:
	v_cvt_pk_bf16_f32 v36, v28, v29
	v_cvt_pk_bf16_f32 v37, v30, v31
	v_cvt_pk_bf16_f32 v38, v24, v25
	v_cvt_pk_bf16_f32 v39, v26, v27
	v_mov_b32_e32 v32, v36
	v_mov_b32_e32 v34, v38
	v_mov_b32_e32 v35, v39
	v_mov_b32_e32 v33, v37
	v_permlane16_swap_b32_e32 v32, v34
	s_nop 0
	v_permlane16_swap_b32_e32 v33, v35
	s_and_saveexec_b64 s[22:23], s[4:5]
	s_xor_b64 s[22:23], exec, s[22:23]
	v_mov_b32_e32 v35, v39
	v_mov_b32_e32 v34, v38
	s_andn2_saveexec_b64 s[22:23], s[22:23]
	v_mov_b32_e32 v32, v36
	v_mov_b32_e32 v33, v37
	s_or_b64 exec, exec, s[22:23]
	v_or_b32_e32 v36, 48, v144
	v_ashrrev_i32_e32 v37, 31, v36
	v_lshlrev_b64 v[38:39], 11, v[36:37]
	v_lshl_add_u64 v[38:39], s[14:15], 0, v[38:39]
	v_lshl_add_u64 v[38:39], s[20:21], 1, v[38:39]
	v_lshl_add_u64 v[40:41], v[142:143], 1, v[38:39]
	s_and_b64 vcc, exec, s[2:3]
	global_store_dwordx4 v[40:41], v[32:35], off
	s_cbranch_vccnz .LBB0_2224
	v_mov_b32_e32 v139, v135
	v_lshl_add_u64 v[32:33], v[140:141], 0, v[138:139]
	v_lshl_add_u64 v[32:33], v[32:33], 0, s[20:21]
	v_lshlrev_b64 v[40:41], 2, v[32:33]
	v_lshl_add_u64 v[32:33], s[8:9], 0, v[40:41]
	v_pk_add_f32 v[18:19], v[18:19], v[208:209]
	v_pk_add_f32 v[16:17], v[16:17], v[206:207]
	v_pk_mul_f32 v[18:19], v[18:19], v[240:241]
	v_pk_mul_f32 v[16:17], v[16:17], v[238:239]

.LBB0_2226:
	v_cvt_pk_bf16_f32 v40, v16, v17
	v_cvt_pk_bf16_f32 v41, v18, v19
	v_cvt_pk_bf16_f32 v42, v12, v13
	v_cvt_pk_bf16_f32 v43, v14, v15
	v_mov_b32_e32 v34, v42
	v_mov_b32_e32 v32, v40
	v_mov_b32_e32 v33, v41
	v_mov_b32_e32 v35, v43
	v_permlane16_swap_b32_e32 v32, v34
	s_nop 0
	v_permlane16_swap_b32_e32 v33, v35
	s_and_saveexec_b64 s[22:23], s[4:5]
	s_xor_b64 s[22:23], exec, s[22:23]
	v_mov_b32_e32 v35, v43
	v_mov_b32_e32 v34, v42
	s_andn2_saveexec_b64 s[22:23], s[22:23]
	v_mov_b32_e32 v32, v40
	v_mov_b32_e32 v33, v41
	s_or_b64 exec, exec, s[22:23]
	v_lshl_add_u64 v[38:39], v[152:153], 1, v[38:39]
	s_and_b64 vcc, exec, s[2:3]
	global_store_dwordx4 v[38:39], v[32:35], off offset:64
	s_cbranch_vccnz .LBB0_2232
	v_mov_b32_e32 v139, v135
	v_lshl_add_u64 v[32:33], v[140:141], 0, v[138:139]
	v_lshl_add_u64 v[32:33], v[32:33], 0, s[20:21]
	v_lshlrev_b64 v[40:41], 2, v[32:33]
	v_lshl_add_u64 v[32:33], s[8:9], 0, v[40:41]
	v_pk_add_f32 v[10:11], v[10:11], v[216:217]
	v_pk_add_f32 v[8:9], v[8:9], v[214:215]
	v_pk_mul_f32 v[10:11], v[10:11], v[248:249]
	v_pk_mul_f32 v[8:9], v[8:9], v[246:247]

.LBB0_2236:
	s_or_b64 exec, exec, s[22:23]
	s_and_b64 vcc, exec, s[2:3]
	global_store_dwordx4 v[38:39], v[32:35], off offset:128
	s_cbranch_vccnz .LBB0_2238

.LBB0_2240:
	v_cvt_pk_bf16_f32 v40, v4, v5
	v_cvt_pk_bf16_f32 v41, v6, v7
	v_cvt_pk_bf16_f32 v42, v20, v21
	v_cvt_pk_bf16_f32 v43, v22, v23
	v_mov_b32_e32 v32, v40
	v_mov_b32_e32 v34, v42
	v_mov_b32_e32 v33, v41
	v_mov_b32_e32 v35, v43
	v_permlane16_swap_b32_e32 v32, v34
	s_nop 0
	v_permlane16_swap_b32_e32 v33, v35
	s_and_saveexec_b64 s[2:3], s[4:5]
	s_xor_b64 s[2:3], exec, s[2:3]
	v_mov_b32_e32 v35, v43
	v_mov_b32_e32 v34, v42
	s_andn2_saveexec_b64 s[2:3], s[2:3]
	v_mov_b32_e32 v32, v40
	v_mov_b32_e32 v33, v41
	s_or_b64 exec, exec, s[2:3]
	v_mul_f32_e32 v9, v9, v9
	v_fmac_f32_e32 v9, v8, v8
	v_fmac_f32_e32 v9, v10, v10
	v_mul_f32_e32 v29, v29, v29
	v_mul_f32_e32 v17, v17, v17
	v_fmac_f32_e32 v9, v11, v11
	v_fmac_f32_e32 v29, v28, v28
	v_fmac_f32_e32 v17, v16, v16
	v_fmac_f32_e32 v9, v0, v0
	v_fmac_f32_e32 v29, v30, v30
	v_fmac_f32_e32 v17, v18, v18
	v_fmac_f32_e32 v9, v1, v1
	v_mul_f32_e32 v1, v5, v5
	v_fmac_f32_e32 v29, v31, v31
	v_fmac_f32_e32 v17, v19, v19
	v_fmac_f32_e32 v1, v4, v4
	v_fmac_f32_e32 v29, v24, v24
	v_fmac_f32_e32 v17, v12, v12
	v_fmac_f32_e32 v1, v6, v6
	v_fmac_f32_e32 v29, v25, v25
	v_fmac_f32_e32 v17, v13, v13
	v_fmac_f32_e32 v1, v7, v7
	v_fmac_f32_e32 v29, v26, v26
	v_fmac_f32_e32 v17, v14, v14
	v_fmac_f32_e32 v1, v20, v20
	v_fmac_f32_e32 v29, v27, v27
	v_fmac_f32_e32 v17, v15, v15
	v_fmac_f32_e32 v9, v2, v2
	v_fmac_f32_e32 v1, v21, v21
	v_add_f32_e32 v12, v29, v17
	v_fmac_f32_e32 v9, v3, v3
	v_fmac_f32_e32 v1, v22, v22
	v_add_f32_e32 v0, v12, v9
	v_fmac_f32_e32 v1, v23, v23
	v_add_f32_e32 v0, v0, v1
	v_mov_b32_e32 v1, v0
	s_nop 1
	v_permlane16_swap_b32_e32 v0, v1
	v_add_f32_e32 v0, v0, v1
	v_mov_b32_e32 v1, v0
	s_nop 1
	v_permlane32_swap_b32_e32 v0, v1
	global_store_dwordx4 v[38:39], v[32:35], off offset:192
	s_and_saveexec_b64 s[2:3], s[6:7]
	s_cbranch_execz .LBB0_2117
	s_lshl_b32 s4, s18, 3
	v_add_f32_e32 v2, v0, v1
	s_sub_i32 s4, s24, s4
	v_lshlrev_b64 v[0:1], 5, v[36:37]
	s_ashr_i32 s5, s4, 31
	v_lshl_add_u64 v[0:1], s[12:13], 0, v[0:1]
	v_lshl_add_u64 v[0:1], s[4:5], 2, v[0:1]
	v_lshl_add_u64 v[0:1], v[136:137], 2, v[0:1]
	global_store_dword v[0:1], v2, off
	s_branch .LBB0_2117

.LBB0_2247:
	v_mov_b32_e32 v128, v134
	v_mov_b32_e32 v129, v139
	s_or_b64 exec, exec, s[6:7]
	s_and_b64 vcc, exec, s[2:3]
	global_store_dwordx4 v[154:155], v[128:131], off offset:128
	s_cbranch_vccz .LBB0_2141
	s_branch .LBB0_2142

.LBB0_2249:
	v_mov_b32_e32 v96, v104
	v_mov_b32_e32 v97, v105
	s_or_b64 exec, exec, s[22:23]
	s_and_b64 vcc, exec, s[2:3]
	global_store_dwordx4 v[102:103], v[96:99], off offset:128
	s_cbranch_vccz .LBB0_2173
	s_branch .LBB0_2174

.LBB0_2251:
	v_mov_b32_e32 v64, v72
	v_mov_b32_e32 v65, v73
	s_or_b64 exec, exec, s[22:23]
	s_and_b64 vcc, exec, s[2:3]
	global_store_dwordx4 v[70:71], v[64:67], off offset:128
	s_cbranch_vccz .LBB0_2205
	s_branch .LBB0_2206

.LBB0_2253:
	v_mov_b32_e32 v32, v40
	v_mov_b32_e32 v33, v41
	s_or_b64 exec, exec, s[22:23]
	s_and_b64 vcc, exec, s[2:3]
	global_store_dwordx4 v[38:39], v[32:35], off offset:128
	s_cbranch_vccz .LBB0_2237
	s_branch .LBB0_2238

.Lg_down_loop:
	ds_read_b128 v[198:201], v134 offset:8192
	ds_read_b128 v[202:205], v134 offset:10240
	ds_read_b128 v[206:209], v134 offset:12288
	ds_read_b128 v[210:213], v134 offset:14336
	s_waitcnt lgkmcnt(4)
	v_mfma_f32_16x16x32_bf16 v[124:127], v[168:171], v[152:155], v[124:127]
	v_mfma_f32_16x16x32_bf16 v[120:123], v[168:171], v[156:159], v[120:123]
	v_mfma_f32_16x16x32_bf16 v[116:119], v[168:171], v[160:163], v[116:119]
	v_mfma_f32_16x16x32_bf16 v[112:115], v[168:171], v[164:167], v[112:115]
	v_mfma_f32_16x16x32_bf16 v[108:111], v[172:175], v[152:155], v[108:111]
	v_mfma_f32_16x16x32_bf16 v[104:107], v[172:175], v[156:159], v[104:107]
	v_mfma_f32_16x16x32_bf16 v[100:103], v[172:175], v[160:163], v[100:103]
	v_mfma_f32_16x16x32_bf16 v[96:99], v[172:175], v[164:167], v[96:99]
	v_mfma_f32_16x16x32_bf16 v[92:95], v[176:179], v[152:155], v[92:95]
	v_mfma_f32_16x16x32_bf16 v[84:87], v[176:179], v[156:159], v[84:87]
	v_mfma_f32_16x16x32_bf16 v[80:83], v[176:179], v[160:163], v[80:83]
	v_mfma_f32_16x16x32_bf16 v[76:79], v[176:179], v[164:167], v[76:79]
	v_mfma_f32_16x16x32_bf16 v[72:75], v[180:183], v[152:155], v[72:75]
	v_mfma_f32_16x16x32_bf16 v[68:71], v[180:183], v[156:159], v[68:71]
	v_mfma_f32_16x16x32_bf16 v[64:67], v[180:183], v[160:163], v[64:67]
	v_mfma_f32_16x16x32_bf16 v[60:63], v[180:183], v[164:167], v[60:63]
	v_add_u32_e32 v180, v150, v149
	v_add_u32_e32 v134, v150, v148
	ds_read_b128 v[168:171], v180 offset:32768
	ds_read_b128 v[172:175], v180 offset:34816
	ds_read_b128 v[176:179], v180 offset:36864
	ds_read_b128 v[180:183], v180 offset:38912
	ds_read_b128 v[214:217], v134 offset:0
	ds_read_b128 v[218:221], v134 offset:2048
	ds_read_b128 v[222:225], v134 offset:4096
	ds_read_b128 v[226:229], v134 offset:6144
	s_waitcnt lgkmcnt(8)
	v_mfma_f32_16x16x32_bf16 v[56:59], v[198:201], v[152:155], v[56:59]
	v_mfma_f32_16x16x32_bf16 v[52:55], v[198:201], v[156:159], v[52:55]
	v_mfma_f32_16x16x32_bf16 v[48:51], v[198:201], v[160:163], v[48:51]
	v_mfma_f32_16x16x32_bf16 v[44:47], v[198:201], v[164:167], v[44:47]
	v_mfma_f32_16x16x32_bf16 v[40:43], v[202:205], v[152:155], v[40:43]
	v_mfma_f32_16x16x32_bf16 v[36:39], v[202:205], v[156:159], v[36:39]
	v_mfma_f32_16x16x32_bf16 v[32:35], v[202:205], v[160:163], v[32:35]
	v_mfma_f32_16x16x32_bf16 v[28:31], v[202:205], v[164:167], v[28:31]
	v_mfma_f32_16x16x32_bf16 v[24:27], v[206:209], v[152:155], v[24:27]
	v_mfma_f32_16x16x32_bf16 v[20:23], v[206:209], v[156:159], v[20:23]
	v_mfma_f32_16x16x32_bf16 v[16:19], v[206:209], v[160:163], v[16:19]
	v_mfma_f32_16x16x32_bf16 v[12:15], v[206:209], v[164:167], v[12:15]
	v_mfma_f32_16x16x32_bf16 v[8:11], v[210:213], v[152:155], v[8:11]
	v_mfma_f32_16x16x32_bf16 v[4:7], v[210:213], v[156:159], v[4:7]
	v_mfma_f32_16x16x32_bf16 v[0:3], v[210:213], v[160:163], v[0:3]
	v_mfma_f32_16x16x32_bf16 v[88:91], v[210:213], v[164:167], v[88:91]
	ds_read_b128 v[152:155], v134 offset:8192
	ds_read_b128 v[156:159], v134 offset:10240
	ds_read_b128 v[160:163], v134 offset:12288
	ds_read_b128 v[164:167], v134 offset:14336
	s_waitcnt lgkmcnt(4)
	v_mfma_f32_16x16x32_bf16 v[124:127], v[214:217], v[168:171], v[124:127]
	v_mfma_f32_16x16x32_bf16 v[120:123], v[214:217], v[172:175], v[120:123]
	v_mfma_f32_16x16x32_bf16 v[116:119], v[214:217], v[176:179], v[116:119]
	v_mfma_f32_16x16x32_bf16 v[112:115], v[214:217], v[180:183], v[112:115]
	v_mfma_f32_16x16x32_bf16 v[108:111], v[218:221], v[168:171], v[108:111]
	v_mfma_f32_16x16x32_bf16 v[104:107], v[218:221], v[172:175], v[104:107]
	v_mfma_f32_16x16x32_bf16 v[100:103], v[218:221], v[176:179], v[100:103]
	v_mfma_f32_16x16x32_bf16 v[96:99], v[218:221], v[180:183], v[96:99]
	v_mfma_f32_16x16x32_bf16 v[92:95], v[222:225], v[168:171], v[92:95]
	v_mfma_f32_16x16x32_bf16 v[84:87], v[222:225], v[172:175], v[84:87]
	v_mfma_f32_16x16x32_bf16 v[80:83], v[222:225], v[176:179], v[80:83]
	v_mfma_f32_16x16x32_bf16 v[76:79], v[222:225], v[180:183], v[76:79]
	v_mfma_f32_16x16x32_bf16 v[72:75], v[226:229], v[168:171], v[72:75]
	v_mfma_f32_16x16x32_bf16 v[68:71], v[226:229], v[172:175], v[68:71]
	v_mfma_f32_16x16x32_bf16 v[64:67], v[226:229], v[176:179], v[64:67]
	v_mfma_f32_16x16x32_bf16 v[60:63], v[226:229], v[180:183], v[60:63]
	s_waitcnt lgkmcnt(0)
	v_mfma_f32_16x16x32_bf16 v[56:59], v[152:155], v[168:171], v[56:59]
	s_waitcnt vmcnt(0)
	s_barrier
	v_add3_u32 v210, v151, v149, s99
	v_add3_u32 v134, v151, v148, s99
	v_mfma_f32_16x16x32_bf16 v[52:55], v[152:155], v[172:175], v[52:55]
	ds_read_b128 v[198:201], v210 offset:32768
	ds_read_b128 v[202:205], v210 offset:34816
	v_mfma_f32_16x16x32_bf16 v[48:51], v[152:155], v[176:179], v[48:51]
	ds_read_b128 v[206:209], v210 offset:36864
	ds_read_b128 v[210:213], v210 offset:38912
	v_mfma_f32_16x16x32_bf16 v[44:47], v[152:155], v[180:183], v[44:47]
	ds_read_b128 v[214:217], v134 offset:0
	ds_read_b128 v[218:221], v134 offset:2048
	v_mfma_f32_16x16x32_bf16 v[40:43], v[156:159], v[168:171], v[40:43]
	ds_read_b128 v[222:225], v134 offset:4096
	ds_read_b128 v[226:229], v134 offset:6144
	s_mov_b32 m0, s12
	v_mfma_f32_16x16x32_bf16 v[36:39], v[156:159], v[172:175], v[36:39]
	global_load_lds_dwordx4 v[128:129], off
	v_lshl_add_u64 v[128:129], v[128:129], 0, s[100:101]
	s_add_i32 m0, s12, 0x8000
	v_mfma_f32_16x16x32_bf16 v[32:35], v[156:159], v[176:179], v[32:35]
	global_load_lds_dwordx4 v[140:141], off
	v_lshl_add_u64 v[140:141], v[140:141], 0, s[100:101]
	s_mov_b32 m0, s13
	v_mfma_f32_16x16x32_bf16 v[28:31], v[156:159], v[180:183], v[28:31]
	global_load_lds_dwordx4 v[130:131], off
	v_lshl_add_u64 v[130:131], v[130:131], 0, s[100:101]
	s_add_i32 m0, s13, 0x8000
	v_mfma_f32_16x16x32_bf16 v[24:27], v[160:163], v[168:171], v[24:27]
	global_load_lds_dwordx4 v[142:143], off
	v_lshl_add_u64 v[142:143], v[142:143], 0, s[100:101]
	s_mov_b32 m0, s29
	v_mfma_f32_16x16x32_bf16 v[20:23], v[160:163], v[172:175], v[20:23]
	global_load_lds_dwordx4 v[136:137], off
	v_lshl_add_u64 v[136:137], v[136:137], 0, s[100:101]
	s_add_i32 m0, s29, 0x8000
	v_mfma_f32_16x16x32_bf16 v[16:19], v[160:163], v[176:179], v[16:19]
	global_load_lds_dwordx4 v[144:145], off
	v_lshl_add_u64 v[144:145], v[144:145], 0, s[100:101]
	s_mov_b32 m0, s31
	v_mfma_f32_16x16x32_bf16 v[12:15], v[160:163], v[180:183], v[12:15]
	global_load_lds_dwordx4 v[138:139], off
	v_lshl_add_u64 v[138:139], v[138:139], 0, s[100:101]
	s_add_i32 m0, s31, 0x8000
	v_mfma_f32_16x16x32_bf16 v[8:11], v[164:167], v[168:171], v[8:11]
	global_load_lds_dwordx4 v[146:147], off
	v_lshl_add_u64 v[146:147], v[146:147], 0, s[100:101]
	v_mfma_f32_16x16x32_bf16 v[4:7], v[164:167], v[172:175], v[4:7]
	v_mfma_f32_16x16x32_bf16 v[0:3], v[164:167], v[176:179], v[0:3]
	v_mfma_f32_16x16x32_bf16 v[88:91], v[164:167], v[180:183], v[88:91]
	ds_read_b128 v[152:155], v134 offset:8192
	ds_read_b128 v[156:159], v134 offset:10240
	ds_read_b128 v[160:163], v134 offset:12288
	ds_read_b128 v[164:167], v134 offset:14336
	s_waitcnt lgkmcnt(4)
	v_mfma_f32_16x16x32_bf16 v[124:127], v[214:217], v[198:201], v[124:127]
	v_mfma_f32_16x16x32_bf16 v[120:123], v[214:217], v[202:205], v[120:123]
	v_mfma_f32_16x16x32_bf16 v[116:119], v[214:217], v[206:209], v[116:119]
	v_mfma_f32_16x16x32_bf16 v[112:115], v[214:217], v[210:213], v[112:115]
	v_mfma_f32_16x16x32_bf16 v[108:111], v[218:221], v[198:201], v[108:111]
	v_mfma_f32_16x16x32_bf16 v[104:107], v[218:221], v[202:205], v[104:107]
	v_mfma_f32_16x16x32_bf16 v[100:103], v[218:221], v[206:209], v[100:103]
	v_mfma_f32_16x16x32_bf16 v[96:99], v[218:221], v[210:213], v[96:99]
	v_mfma_f32_16x16x32_bf16 v[92:95], v[222:225], v[198:201], v[92:95]
	v_mfma_f32_16x16x32_bf16 v[84:87], v[222:225], v[202:205], v[84:87]
	v_mfma_f32_16x16x32_bf16 v[80:83], v[222:225], v[206:209], v[80:83]
	v_mfma_f32_16x16x32_bf16 v[76:79], v[222:225], v[210:213], v[76:79]
	v_mfma_f32_16x16x32_bf16 v[72:75], v[226:229], v[198:201], v[72:75]
	v_mfma_f32_16x16x32_bf16 v[68:71], v[226:229], v[202:205], v[68:71]
	v_mfma_f32_16x16x32_bf16 v[64:67], v[226:229], v[206:209], v[64:67]
	v_mfma_f32_16x16x32_bf16 v[60:63], v[226:229], v[210:213], v[60:63]
	v_add3_u32 v226, v150, v149, s99
	v_add3_u32 v134, v150, v148, s99
	ds_read_b128 v[214:217], v226 offset:32768
	ds_read_b128 v[218:221], v226 offset:34816
	ds_read_b128 v[222:225], v226 offset:36864
	ds_read_b128 v[226:229], v226 offset:38912
	ds_read_b128 v[168:171], v134 offset:0
	ds_read_b128 v[172:175], v134 offset:2048
	ds_read_b128 v[176:179], v134 offset:4096
	ds_read_b128 v[180:183], v134 offset:6144
	s_waitcnt lgkmcnt(8)
	v_mfma_f32_16x16x32_bf16 v[56:59], v[152:155], v[198:201], v[56:59]
	v_mfma_f32_16x16x32_bf16 v[52:55], v[152:155], v[202:205], v[52:55]
	v_mfma_f32_16x16x32_bf16 v[48:51], v[152:155], v[206:209], v[48:51]
	v_mfma_f32_16x16x32_bf16 v[44:47], v[152:155], v[210:213], v[44:47]
	v_mfma_f32_16x16x32_bf16 v[40:43], v[156:159], v[198:201], v[40:43]
	v_mfma_f32_16x16x32_bf16 v[36:39], v[156:159], v[202:205], v[36:39]
	v_mfma_f32_16x16x32_bf16 v[32:35], v[156:159], v[206:209], v[32:35]
	v_mfma_f32_16x16x32_bf16 v[28:31], v[156:159], v[210:213], v[28:31]
	v_mfma_f32_16x16x32_bf16 v[24:27], v[160:163], v[198:201], v[24:27]
	v_mfma_f32_16x16x32_bf16 v[20:23], v[160:163], v[202:205], v[20:23]
	v_mfma_f32_16x16x32_bf16 v[16:19], v[160:163], v[206:209], v[16:19]
	v_mfma_f32_16x16x32_bf16 v[12:15], v[160:163], v[210:213], v[12:15]
	v_mfma_f32_16x16x32_bf16 v[8:11], v[164:167], v[198:201], v[8:11]
	v_mfma_f32_16x16x32_bf16 v[4:7], v[164:167], v[202:205], v[4:7]
	v_mfma_f32_16x16x32_bf16 v[0:3], v[164:167], v[206:209], v[0:3]
	v_mfma_f32_16x16x32_bf16 v[88:91], v[164:167], v[210:213], v[88:91]
	ds_read_b128 v[198:201], v134 offset:8192
	ds_read_b128 v[202:205], v134 offset:10240
	ds_read_b128 v[206:209], v134 offset:12288
	ds_read_b128 v[210:213], v134 offset:14336
	s_waitcnt lgkmcnt(4)
	v_mfma_f32_16x16x32_bf16 v[124:127], v[168:171], v[214:217], v[124:127]
	v_mfma_f32_16x16x32_bf16 v[120:123], v[168:171], v[218:221], v[120:123]
	v_mfma_f32_16x16x32_bf16 v[116:119], v[168:171], v[222:225], v[116:119]
	v_mfma_f32_16x16x32_bf16 v[112:115], v[168:171], v[226:229], v[112:115]
	v_mfma_f32_16x16x32_bf16 v[108:111], v[172:175], v[214:217], v[108:111]
	v_mfma_f32_16x16x32_bf16 v[104:107], v[172:175], v[218:221], v[104:107]
	v_mfma_f32_16x16x32_bf16 v[100:103], v[172:175], v[222:225], v[100:103]
	v_mfma_f32_16x16x32_bf16 v[96:99], v[172:175], v[226:229], v[96:99]
	v_mfma_f32_16x16x32_bf16 v[92:95], v[176:179], v[214:217], v[92:95]
	v_mfma_f32_16x16x32_bf16 v[84:87], v[176:179], v[218:221], v[84:87]
	v_mfma_f32_16x16x32_bf16 v[80:83], v[176:179], v[222:225], v[80:83]
	v_mfma_f32_16x16x32_bf16 v[76:79], v[176:179], v[226:229], v[76:79]
	v_mfma_f32_16x16x32_bf16 v[72:75], v[180:183], v[214:217], v[72:75]
	v_mfma_f32_16x16x32_bf16 v[68:71], v[180:183], v[218:221], v[68:71]
	v_mfma_f32_16x16x32_bf16 v[64:67], v[180:183], v[222:225], v[64:67]
	v_mfma_f32_16x16x32_bf16 v[60:63], v[180:183], v[226:229], v[60:63]
	s_waitcnt lgkmcnt(0)
	v_mfma_f32_16x16x32_bf16 v[56:59], v[198:201], v[214:217], v[56:59]
	s_waitcnt vmcnt(0)
	s_barrier
	v_add_u32_e32 v164, v151, v149
	v_add_u32_e32 v134, v151, v148
	v_mfma_f32_16x16x32_bf16 v[52:55], v[198:201], v[218:221], v[52:55]
	ds_read_b128 v[152:155], v164 offset:32768
	ds_read_b128 v[156:159], v164 offset:34816
	v_mfma_f32_16x16x32_bf16 v[48:51], v[198:201], v[222:225], v[48:51]
	ds_read_b128 v[160:163], v164 offset:36864
	ds_read_b128 v[164:167], v164 offset:38912
	v_mfma_f32_16x16x32_bf16 v[44:47], v[198:201], v[226:229], v[44:47]
	ds_read_b128 v[168:171], v134 offset:0
	ds_read_b128 v[172:175], v134 offset:2048
	v_mfma_f32_16x16x32_bf16 v[40:43], v[202:205], v[214:217], v[40:43]
	ds_read_b128 v[176:179], v134 offset:4096
	ds_read_b128 v[180:183], v134 offset:6144
	s_add_i32 m0, s12, 0x10000
	v_mfma_f32_16x16x32_bf16 v[36:39], v[202:205], v[218:221], v[36:39]
	global_load_lds_dwordx4 v[128:129], off
	v_lshl_add_u64 v[128:129], v[128:129], 0, s[100:101]
	s_add_i32 m0, s12, 0x18000
	v_mfma_f32_16x16x32_bf16 v[32:35], v[202:205], v[222:225], v[32:35]
	global_load_lds_dwordx4 v[140:141], off
	v_lshl_add_u64 v[140:141], v[140:141], 0, s[100:101]
	s_add_i32 m0, s13, 0x10000
	v_mfma_f32_16x16x32_bf16 v[28:31], v[202:205], v[226:229], v[28:31]
	global_load_lds_dwordx4 v[130:131], off
	v_lshl_add_u64 v[130:131], v[130:131], 0, s[100:101]
	s_add_i32 m0, s13, 0x18000
	v_mfma_f32_16x16x32_bf16 v[24:27], v[206:209], v[214:217], v[24:27]
	global_load_lds_dwordx4 v[142:143], off
	v_lshl_add_u64 v[142:143], v[142:143], 0, s[100:101]
	s_add_i32 m0, s29, 0x10000
	v_mfma_f32_16x16x32_bf16 v[20:23], v[206:209], v[218:221], v[20:23]
	global_load_lds_dwordx4 v[136:137], off
	v_lshl_add_u64 v[136:137], v[136:137], 0, s[100:101]
	s_add_i32 m0, s29, 0x18000
	v_mfma_f32_16x16x32_bf16 v[16:19], v[206:209], v[222:225], v[16:19]
	global_load_lds_dwordx4 v[144:145], off
	v_lshl_add_u64 v[144:145], v[144:145], 0, s[100:101]
	s_add_i32 m0, s31, 0x10000
	v_mfma_f32_16x16x32_bf16 v[12:15], v[206:209], v[226:229], v[12:15]
	global_load_lds_dwordx4 v[138:139], off
	v_lshl_add_u64 v[138:139], v[138:139], 0, s[100:101]
	s_add_i32 m0, s31, 0x18000
	v_mfma_f32_16x16x32_bf16 v[8:11], v[210:213], v[214:217], v[8:11]
	global_load_lds_dwordx4 v[146:147], off
	v_lshl_add_u64 v[146:147], v[146:147], 0, s[100:101]
	v_mfma_f32_16x16x32_bf16 v[4:7], v[210:213], v[218:221], v[4:7]
	v_mfma_f32_16x16x32_bf16 v[0:3], v[210:213], v[222:225], v[0:3]
	v_mfma_f32_16x16x32_bf16 v[88:91], v[210:213], v[226:229], v[88:91]
	s_add_u32 s4, s4, 0x100
	s_cmpk_lg_i32 s4, 0x1500
	s_cbranch_scc1 .Lg_down_loop
	ds_read_b128 v[198:201], v134 offset:8192
	ds_read_b128 v[202:205], v134 offset:10240
	ds_read_b128 v[206:209], v134 offset:12288
	ds_read_b128 v[210:213], v134 offset:14336
	s_waitcnt lgkmcnt(4)
	v_mfma_f32_16x16x32_bf16 v[124:127], v[168:171], v[152:155], v[124:127]
	v_mfma_f32_16x16x32_bf16 v[120:123], v[168:171], v[156:159], v[120:123]
	v_mfma_f32_16x16x32_bf16 v[116:119], v[168:171], v[160:163], v[116:119]
	v_mfma_f32_16x16x32_bf16 v[112:115], v[168:171], v[164:167], v[112:115]
	v_mfma_f32_16x16x32_bf16 v[108:111], v[172:175], v[152:155], v[108:111]
	v_mfma_f32_16x16x32_bf16 v[104:107], v[172:175], v[156:159], v[104:107]
	v_mfma_f32_16x16x32_bf16 v[100:103], v[172:175], v[160:163], v[100:103]
	v_mfma_f32_16x16x32_bf16 v[96:99], v[172:175], v[164:167], v[96:99]
	v_mfma_f32_16x16x32_bf16 v[92:95], v[176:179], v[152:155], v[92:95]
	v_mfma_f32_16x16x32_bf16 v[84:87], v[176:179], v[156:159], v[84:87]
	v_mfma_f32_16x16x32_bf16 v[80:83], v[176:179], v[160:163], v[80:83]
	v_mfma_f32_16x16x32_bf16 v[76:79], v[176:179], v[164:167], v[76:79]
	v_mfma_f32_16x16x32_bf16 v[72:75], v[180:183], v[152:155], v[72:75]
	v_mfma_f32_16x16x32_bf16 v[68:71], v[180:183], v[156:159], v[68:71]
	v_mfma_f32_16x16x32_bf16 v[64:67], v[180:183], v[160:163], v[64:67]
	v_mfma_f32_16x16x32_bf16 v[60:63], v[180:183], v[164:167], v[60:63]
	v_add_u32_e32 v180, v150, v149
	v_add_u32_e32 v134, v150, v148
	ds_read_b128 v[168:171], v180 offset:32768
	ds_read_b128 v[172:175], v180 offset:34816
	ds_read_b128 v[176:179], v180 offset:36864
	ds_read_b128 v[180:183], v180 offset:38912
	ds_read_b128 v[214:217], v134 offset:0
	ds_read_b128 v[218:221], v134 offset:2048
	ds_read_b128 v[222:225], v134 offset:4096
	ds_read_b128 v[226:229], v134 offset:6144
	s_waitcnt lgkmcnt(8)
	v_mfma_f32_16x16x32_bf16 v[56:59], v[198:201], v[152:155], v[56:59]
	v_mfma_f32_16x16x32_bf16 v[52:55], v[198:201], v[156:159], v[52:55]
	v_mfma_f32_16x16x32_bf16 v[48:51], v[198:201], v[160:163], v[48:51]
	v_mfma_f32_16x16x32_bf16 v[44:47], v[198:201], v[164:167], v[44:47]
	v_mfma_f32_16x16x32_bf16 v[40:43], v[202:205], v[152:155], v[40:43]
	v_mfma_f32_16x16x32_bf16 v[36:39], v[202:205], v[156:159], v[36:39]
	v_mfma_f32_16x16x32_bf16 v[32:35], v[202:205], v[160:163], v[32:35]
	v_mfma_f32_16x16x32_bf16 v[28:31], v[202:205], v[164:167], v[28:31]
	v_mfma_f32_16x16x32_bf16 v[24:27], v[206:209], v[152:155], v[24:27]
	v_mfma_f32_16x16x32_bf16 v[20:23], v[206:209], v[156:159], v[20:23]
	v_mfma_f32_16x16x32_bf16 v[16:19], v[206:209], v[160:163], v[16:19]
	v_mfma_f32_16x16x32_bf16 v[12:15], v[206:209], v[164:167], v[12:15]
	v_mfma_f32_16x16x32_bf16 v[8:11], v[210:213], v[152:155], v[8:11]
	v_mfma_f32_16x16x32_bf16 v[4:7], v[210:213], v[156:159], v[4:7]
	v_mfma_f32_16x16x32_bf16 v[0:3], v[210:213], v[160:163], v[0:3]
	v_mfma_f32_16x16x32_bf16 v[88:91], v[210:213], v[164:167], v[88:91]
	ds_read_b128 v[152:155], v134 offset:8192
	ds_read_b128 v[156:159], v134 offset:10240
	ds_read_b128 v[160:163], v134 offset:12288
	ds_read_b128 v[164:167], v134 offset:14336
	s_waitcnt lgkmcnt(4)
	v_mfma_f32_16x16x32_bf16 v[124:127], v[214:217], v[168:171], v[124:127]
	v_mfma_f32_16x16x32_bf16 v[120:123], v[214:217], v[172:175], v[120:123]
	v_mfma_f32_16x16x32_bf16 v[116:119], v[214:217], v[176:179], v[116:119]
	v_mfma_f32_16x16x32_bf16 v[112:115], v[214:217], v[180:183], v[112:115]
	v_mfma_f32_16x16x32_bf16 v[108:111], v[218:221], v[168:171], v[108:111]
	v_mfma_f32_16x16x32_bf16 v[104:107], v[218:221], v[172:175], v[104:107]
	v_mfma_f32_16x16x32_bf16 v[100:103], v[218:221], v[176:179], v[100:103]
	v_mfma_f32_16x16x32_bf16 v[96:99], v[218:221], v[180:183], v[96:99]
	v_mfma_f32_16x16x32_bf16 v[92:95], v[222:225], v[168:171], v[92:95]
	v_mfma_f32_16x16x32_bf16 v[84:87], v[222:225], v[172:175], v[84:87]
	v_mfma_f32_16x16x32_bf16 v[80:83], v[222:225], v[176:179], v[80:83]
	v_mfma_f32_16x16x32_bf16 v[76:79], v[222:225], v[180:183], v[76:79]
	v_mfma_f32_16x16x32_bf16 v[72:75], v[226:229], v[168:171], v[72:75]
	v_mfma_f32_16x16x32_bf16 v[68:71], v[226:229], v[172:175], v[68:71]
	v_mfma_f32_16x16x32_bf16 v[64:67], v[226:229], v[176:179], v[64:67]
	v_mfma_f32_16x16x32_bf16 v[60:63], v[226:229], v[180:183], v[60:63]
	s_waitcnt lgkmcnt(0)
	v_mfma_f32_16x16x32_bf16 v[56:59], v[152:155], v[168:171], v[56:59]
	s_waitcnt vmcnt(0)
	s_barrier
	v_mfma_f32_16x16x32_bf16 v[52:55], v[152:155], v[172:175], v[52:55]
	v_mfma_f32_16x16x32_bf16 v[48:51], v[152:155], v[176:179], v[48:51]
	v_mfma_f32_16x16x32_bf16 v[44:47], v[152:155], v[180:183], v[44:47]
	v_mfma_f32_16x16x32_bf16 v[40:43], v[156:159], v[168:171], v[40:43]
	v_mfma_f32_16x16x32_bf16 v[36:39], v[156:159], v[172:175], v[36:39]
	v_mfma_f32_16x16x32_bf16 v[32:35], v[156:159], v[176:179], v[32:35]
	v_mfma_f32_16x16x32_bf16 v[28:31], v[156:159], v[180:183], v[28:31]
	v_mfma_f32_16x16x32_bf16 v[24:27], v[160:163], v[168:171], v[24:27]
	v_mfma_f32_16x16x32_bf16 v[20:23], v[160:163], v[172:175], v[20:23]
	v_mfma_f32_16x16x32_bf16 v[16:19], v[160:163], v[176:179], v[16:19]
	v_mfma_f32_16x16x32_bf16 v[12:15], v[160:163], v[180:183], v[12:15]
	v_mfma_f32_16x16x32_bf16 v[8:11], v[164:167], v[168:171], v[8:11]
	v_mfma_f32_16x16x32_bf16 v[4:7], v[164:167], v[172:175], v[4:7]
	v_mfma_f32_16x16x32_bf16 v[0:3], v[164:167], v[176:179], v[0:3]
	v_mfma_f32_16x16x32_bf16 v[88:91], v[164:167], v[180:183], v[88:91]
	s_movk_i32 s4, 0x1580
	s_mov_b32 s86, 0x10000
	s_mov_b32 s87, 0x2b0000
	s_mov_b32 s44, 0x2b0000
	v_add_u32_e32 v134, s86, v151
	v_add_u32_e32 v144, v134, v149
	v_add_u32_e32 v134, v134, v148
	ds_read_b128 v[128:131], v144 offset:32768
	ds_read_b128 v[136:139], v144 offset:34816
	ds_read_b128 v[140:143], v144 offset:36864
	ds_read_b128 v[144:147], v144 offset:38912
	ds_read_b128 v[152:155], v134
	ds_read_b128 v[156:159], v134 offset:2048
	ds_read_b128 v[160:163], v134 offset:4096
	ds_read_b128 v[164:167], v134 offset:6144
	ds_read_b128 v[168:171], v134 offset:8192
	ds_read_b128 v[172:175], v134 offset:10240
	ds_read_b128 v[176:179], v134 offset:12288
	ds_read_b128 v[180:183], v134 offset:14336
	s_waitcnt lgkmcnt(0)
	v_mfma_f32_16x16x32_bf16 v[124:127], v[152:155], v[128:131], v[124:127]
	v_mfma_f32_16x16x32_bf16 v[120:123], v[152:155], v[136:139], v[120:123]
	v_mfma_f32_16x16x32_bf16 v[116:119], v[152:155], v[140:143], v[116:119]
	v_mfma_f32_16x16x32_bf16 v[112:115], v[152:155], v[144:147], v[112:115]
	v_mfma_f32_16x16x32_bf16 v[108:111], v[156:159], v[128:131], v[108:111]
	v_mfma_f32_16x16x32_bf16 v[104:107], v[156:159], v[136:139], v[104:107]
	v_mfma_f32_16x16x32_bf16 v[100:103], v[156:159], v[140:143], v[100:103]
	v_mfma_f32_16x16x32_bf16 v[96:99], v[156:159], v[144:147], v[96:99]
	v_mfma_f32_16x16x32_bf16 v[84:87], v[160:163], v[136:139], v[84:87]
	v_mfma_f32_16x16x32_bf16 v[76:79], v[160:163], v[144:147], v[76:79]
	v_mfma_f32_16x16x32_bf16 v[72:75], v[164:167], v[128:131], v[72:75]
	v_mfma_f32_16x16x32_bf16 v[68:71], v[164:167], v[136:139], v[68:71]
	v_mfma_f32_16x16x32_bf16 v[64:67], v[164:167], v[140:143], v[64:67]
	v_mfma_f32_16x16x32_bf16 v[152:155], v[160:163], v[128:131], v[92:95]
	v_mfma_f32_16x16x32_bf16 v[156:159], v[160:163], v[140:143], v[80:83]
	v_mfma_f32_16x16x32_bf16 v[160:163], v[164:167], v[144:147], v[60:63]
	s_nop 2
	v_add_u32_e32 v60, s86, v150
	v_add_u32_e32 v61, v60, v149
	v_add_u32_e32 v60, v60, v148
	ds_read_b128 v[164:167], v61 offset:32768
	ds_read_b128 v[198:201], v61 offset:34816
	ds_read_b128 v[202:205], v61 offset:36864
	ds_read_b128 v[206:209], v61 offset:38912
	ds_read_b128 v[80:83], v60
	ds_read_b128 v[148:151], v60 offset:2048
	ds_read_b128 v[210:213], v60 offset:4096
	ds_read_b128 v[214:217], v60 offset:6144
	v_mfma_f32_16x16x32_bf16 v[56:59], v[168:171], v[128:131], v[56:59]
	v_mfma_f32_16x16x32_bf16 v[218:221], v[168:171], v[136:139], v[52:55]
	v_mfma_f32_16x16x32_bf16 v[222:225], v[168:171], v[140:143], v[48:51]
	v_mfma_f32_16x16x32_bf16 v[44:47], v[168:171], v[144:147], v[44:47]
	v_mfma_f32_16x16x32_bf16 v[168:171], v[172:175], v[128:131], v[40:43]
	v_mfma_f32_16x16x32_bf16 v[226:229], v[172:175], v[136:139], v[36:39]
	v_mfma_f32_16x16x32_bf16 v[32:35], v[172:175], v[140:143], v[32:35]
	v_mfma_f32_16x16x32_bf16 v[28:31], v[172:175], v[144:147], v[28:31]
	v_mfma_f32_16x16x32_bf16 v[172:175], v[176:179], v[128:131], v[24:27]
	v_mfma_f32_16x16x32_bf16 v[16:19], v[176:179], v[140:143], v[16:19]
	v_mfma_f32_16x16x32_bf16 v[128:131], v[180:183], v[128:131], v[8:11]
	v_mfma_f32_16x16x32_bf16 v[230:233], v[176:179], v[136:139], v[20:23]
	v_mfma_f32_16x16x32_bf16 v[176:179], v[176:179], v[144:147], v[12:15]
	v_mfma_f32_16x16x32_bf16 v[234:237], v[180:183], v[136:139], v[4:7]
	v_mfma_f32_16x16x32_bf16 v[140:143], v[180:183], v[140:143], v[0:3]
	v_mfma_f32_16x16x32_bf16 v[144:147], v[180:183], v[144:147], v[88:91]
	s_nop 1
	ds_read_b128 v[0:3], v60 offset:8192
	ds_read_b128 v[136:139], v60 offset:10240
	ds_read_b128 v[180:183], v60 offset:12288
	ds_read_b128 v[238:241], v60 offset:14336
	s_waitcnt lgkmcnt(0)
	v_mfma_f32_16x16x32_bf16 v[124:127], v[80:83], v[164:167], v[124:127]
	v_mfma_f32_16x16x32_bf16 v[92:95], v[80:83], v[198:201], v[120:123]
	v_mfma_f32_16x16x32_bf16 v[60:63], v[80:83], v[202:205], v[116:119]
	v_mfma_f32_16x16x32_bf16 v[24:27], v[80:83], v[206:209], v[112:115]
	v_mfma_f32_16x16x32_bf16 v[120:123], v[148:151], v[164:167], v[108:111]
	v_mfma_f32_16x16x32_bf16 v[88:91], v[148:151], v[198:201], v[104:107]
	v_mfma_f32_16x16x32_bf16 v[52:55], v[148:151], v[202:205], v[100:103]
	v_mfma_f32_16x16x32_bf16 v[20:23], v[148:151], v[206:209], v[96:99]
	v_mfma_f32_16x16x32_bf16 v[116:119], v[210:213], v[164:167], v[152:155]
	v_mfma_f32_16x16x32_bf16 v[80:83], v[210:213], v[198:201], v[84:87]
	v_mfma_f32_16x16x32_bf16 v[48:51], v[210:213], v[202:205], v[156:159]
	v_mfma_f32_16x16x32_bf16 v[12:15], v[210:213], v[206:209], v[76:79]
	v_mfma_f32_16x16x32_bf16 v[108:111], v[214:217], v[164:167], v[72:75]
	v_mfma_f32_16x16x32_bf16 v[76:79], v[214:217], v[198:201], v[68:71]
	v_mfma_f32_16x16x32_bf16 v[40:43], v[214:217], v[202:205], v[64:67]
	v_mfma_f32_16x16x32_bf16 v[8:11], v[214:217], v[206:209], v[160:163]
	v_mfma_f32_16x16x32_bf16 v[104:107], v[0:3], v[164:167], v[56:59]
	s_waitcnt vmcnt(0)
	s_waitcnt lgkmcnt(0)
	s_barrier
	v_mfma_f32_16x16x32_bf16 v[68:71], v[0:3], v[198:201], v[218:221]
	v_cvt_pk_bf16_f32 v134, v124, v125
	v_mfma_f32_16x16x32_bf16 v[36:39], v[0:3], v[202:205], v[222:225]
	v_mfma_f32_16x16x32_bf16 v[4:7], v[0:3], v[206:209], v[44:47]
	v_mfma_f32_16x16x32_bf16 v[100:103], v[136:139], v[164:167], v[168:171]
	v_mfma_f32_16x16x32_bf16 v[64:67], v[136:139], v[198:201], v[226:229]
	v_mfma_f32_16x16x32_bf16 v[32:35], v[136:139], v[202:205], v[32:35]
	v_mfma_f32_16x16x32_bf16 v[0:3], v[136:139], v[206:209], v[28:31]
	v_mov_b32_e32 v137, v184
	v_cvt_pk_bf16_f32 v136, v126, v127
	v_mfma_f32_16x16x32_bf16 v[96:99], v[180:183], v[164:167], v[172:175]
	v_and_b32_e32 v28, 16, v137
	v_cmp_eq_u32_e64 s[4:5], 0, v28
	v_cmp_ne_u32_e32 vcc, 0, v28
	v_mfma_f32_16x16x32_bf16 v[72:75], v[180:183], v[198:201], v[230:233]
	v_cvt_pk_bf16_f32 v138, v120, v121
	v_cvt_pk_bf16_f32 v139, v122, v123
	v_mfma_f32_16x16x32_bf16 v[44:47], v[180:183], v[202:205], v[16:19]
	v_mfma_f32_16x16x32_bf16 v[16:19], v[180:183], v[206:209], v[176:179]
	v_mfma_f32_16x16x32_bf16 v[112:115], v[238:241], v[164:167], v[128:131]
	v_mfma_f32_16x16x32_bf16 v[84:87], v[238:241], v[198:201], v[234:237]
	s_nop 1
	v_mov_b32_e32 v128, v134
	v_mov_b32_e32 v130, v138
	v_mov_b32_e32 v131, v139
	v_mfma_f32_16x16x32_bf16 v[56:59], v[238:241], v[202:205], v[140:143]
	v_mov_b32_e32 v129, v136
	v_permlane16_swap_b32_e32 v128, v130
	v_mfma_f32_16x16x32_bf16 v[28:31], v[238:241], v[206:209], v[144:147]
	v_permlane16_swap_b32_e32 v129, v131
	s_and_saveexec_b64 s[12:13], vcc
	s_xor_b64 s[12:13], exec, s[12:13]
	v_mov_b32_e32 v131, v139
	v_mov_b32_e32 v130, v138
	s_andn2_saveexec_b64 s[12:13], s[12:13]
	v_mov_b32_e32 v128, v134
	v_mov_b32_e32 v129, v136
	s_or_b64 exec, exec, s[12:13]
	v_ashrrev_i32_e32 v136, 8, v137
	v_bfe_u32 v134, v137, 4, 2
	v_and_b32_e32 v137, 0xcf, v137
	v_lshlrev_b32_e32 v138, 2, v134
	v_lshl_or_b32 v140, s22, 8, v137
	v_add_u32_e32 v139, 12, v138
	v_ashrrev_i32_e32 v141, 31, v140
	v_cndmask_b32_e64 v138, v139, v138, s[4:5]
	v_lshlrev_b64 v[142:143], 11, v[140:141]
	s_lshl_b32 s44, s24, 8
	v_lshl_or_b32 v138, v136, 7, v138
	v_lshl_add_u64 v[142:143], s[8:9], 0, v[142:143]
	v_lshl_add_u64 v[142:143], s[44:45], 1, v[142:143]
	v_ashrrev_i32_e32 v139, 31, v138
	v_lshl_add_u64 v[142:143], v[138:139], 1, v[142:143]
	v_cvt_pk_bf16_f32 v137, v116, v117
	v_cvt_pk_bf16_f32 v144, v118, v119
	v_cvt_pk_bf16_f32 v145, v108, v109
	v_cvt_pk_bf16_f32 v146, v110, v111
	global_store_dwordx4 v[142:143], v[128:131], off
	s_nop 1
	v_mov_b32_e32 v128, v137
	v_mov_b32_e32 v130, v145
	v_mov_b32_e32 v129, v144
	v_mov_b32_e32 v131, v146
	v_permlane16_swap_b32_e32 v128, v130
	s_nop 0
	v_permlane16_swap_b32_e32 v129, v131
	s_and_saveexec_b64 s[4:5], vcc
	s_xor_b64 s[4:5], exec, s[4:5]
	v_mov_b32_e32 v131, v146
	v_mov_b32_e32 v130, v145
	s_andn2_saveexec_b64 s[4:5], s[4:5]
	v_mov_b32_e32 v128, v137
	v_mov_b32_e32 v129, v144
	s_or_b64 exec, exec, s[4:5]
	v_cvt_pk_bf16_f32 v137, v104, v105
	v_cvt_pk_bf16_f32 v144, v106, v107
	v_cvt_pk_bf16_f32 v145, v100, v101
	v_cvt_pk_bf16_f32 v146, v102, v103
	global_store_dwordx4 v[142:143], v[128:131], off offset:64
	s_nop 1
	v_mov_b32_e32 v128, v137
	v_mov_b32_e32 v130, v145
	v_mov_b32_e32 v129, v144
	v_mov_b32_e32 v131, v146
	v_permlane16_swap_b32_e32 v128, v130
	s_nop 0
	v_permlane16_swap_b32_e32 v129, v131
	s_and_saveexec_b64 s[4:5], vcc
	s_xor_b64 s[4:5], exec, s[4:5]
	v_mov_b32_e32 v131, v146
	v_mov_b32_e32 v130, v145
	s_andn2_saveexec_b64 s[4:5], s[4:5]
	v_mov_b32_e32 v128, v137
	v_mov_b32_e32 v129, v144
	s_or_b64 exec, exec, s[4:5]
	v_cvt_pk_bf16_f32 v137, v96, v97
	v_cvt_pk_bf16_f32 v144, v98, v99
	v_cvt_pk_bf16_f32 v145, v112, v113
	v_cvt_pk_bf16_f32 v146, v114, v115
	global_store_dwordx4 v[142:143], v[128:131], off offset:128
	s_nop 1
	v_mov_b32_e32 v128, v137
	v_mov_b32_e32 v130, v145
	v_mov_b32_e32 v129, v144
	v_mov_b32_e32 v131, v146
	v_permlane16_swap_b32_e32 v128, v130
	s_nop 0
	v_permlane16_swap_b32_e32 v129, v131
	s_and_saveexec_b64 s[4:5], vcc
	s_xor_b64 s[4:5], exec, s[4:5]
	v_mov_b32_e32 v131, v146
	v_mov_b32_e32 v130, v145
	s_andn2_saveexec_b64 s[4:5], s[4:5]
	v_mov_b32_e32 v128, v137
	v_mov_b32_e32 v129, v144
	s_or_b64 exec, exec, s[4:5]
	v_mul_f32_e32 v125, v125, v125
	v_mul_f32_e32 v117, v117, v117
	v_fmac_f32_e32 v125, v124, v124
	v_fmac_f32_e32 v117, v116, v116
	v_mul_f32_e32 v105, v105, v105
	v_fmac_f32_e32 v125, v126, v126
	v_fmac_f32_e32 v117, v118, v118
	v_fmac_f32_e32 v105, v104, v104
	v_mul_f32_e32 v97, v97, v97
	v_fmac_f32_e32 v125, v127, v127
	v_fmac_f32_e32 v117, v119, v119
	v_fmac_f32_e32 v105, v106, v106
	v_fmac_f32_e32 v97, v96, v96
	v_fmac_f32_e32 v125, v120, v120
	v_fmac_f32_e32 v117, v108, v108
	v_fmac_f32_e32 v105, v107, v107
	v_fmac_f32_e32 v97, v98, v98
	v_fmac_f32_e32 v125, v121, v121
	v_fmac_f32_e32 v117, v109, v109
	v_fmac_f32_e32 v105, v100, v100
	v_fmac_f32_e32 v97, v99, v99
	v_fmac_f32_e32 v125, v122, v122
	v_fmac_f32_e32 v117, v110, v110
	v_fmac_f32_e32 v105, v101, v101
	v_fmac_f32_e32 v97, v112, v112
	v_fmac_f32_e32 v125, v123, v123
	v_fmac_f32_e32 v117, v111, v111
	v_fmac_f32_e32 v105, v102, v102
	v_fmac_f32_e32 v97, v113, v113
	v_add_f32_e32 v108, v125, v117
	v_fmac_f32_e32 v105, v103, v103
	v_fmac_f32_e32 v97, v114, v114
	v_add_f32_e32 v100, v108, v105
	v_fmac_f32_e32 v97, v115, v115
	v_add_f32_e32 v96, v100, v97
	v_mov_b32_e32 v97, v96
	s_nop 1
	v_permlane16_swap_b32_e32 v96, v97
	v_add_f32_e32 v96, v96, v97
	v_mov_b32_e32 v97, v96
	v_cmp_eq_u32_e64 s[4:5], 0, v134
	v_ashrrev_i32_e32 v137, 31, v136
	v_permlane32_swap_b32_e32 v96, v97
	global_store_dwordx4 v[142:143], v[128:131], off offset:192
	s_and_saveexec_b64 s[12:13], s[4:5]
	s_cbranch_execz .LBB0_2374
	v_add_f32_e32 v98, v96, v97
	v_lshlrev_b64 v[96:97], 5, v[140:141]
	s_lshl_b32 s86, s24, 1
	s_mov_b32 s87, s45
	v_lshl_add_u64 v[96:97], s[10:11], 0, v[96:97]
	v_lshl_add_u64 v[96:97], s[86:87], 2, v[96:97]
	v_lshl_add_u64 v[96:97], v[136:137], 2, v[96:97]
	global_store_dword v[96:97], v98, off
.LBB0_2374:
	s_or_b64 exec, exec, s[12:13]
	v_cvt_pk_bf16_f32 v100, v92, v93
	v_cvt_pk_bf16_f32 v101, v94, v95
	v_cvt_pk_bf16_f32 v102, v88, v89
	v_cvt_pk_bf16_f32 v103, v90, v91
	v_mov_b32_e32 v96, v100
	v_mov_b32_e32 v98, v102
	v_mov_b32_e32 v99, v103
	v_mov_b32_e32 v97, v101
	v_permlane16_swap_b32_e32 v96, v98
	s_nop 0
	v_permlane16_swap_b32_e32 v97, v99
	s_and_saveexec_b64 s[12:13], vcc
	s_xor_b64 s[12:13], exec, s[12:13]
	v_mov_b32_e32 v99, v103
	v_mov_b32_e32 v98, v102
	s_andn2_saveexec_b64 s[12:13], s[12:13]
	v_mov_b32_e32 v96, v100
	v_mov_b32_e32 v97, v101
	s_or_b64 exec, exec, s[12:13]
	v_or_b32_e32 v100, 16, v140
	v_ashrrev_i32_e32 v101, 31, v100
	v_lshlrev_b64 v[102:103], 11, v[100:101]
	v_lshl_add_u64 v[102:103], s[8:9], 0, v[102:103]
	v_lshl_add_u64 v[102:103], s[44:45], 1, v[102:103]
	v_lshl_add_u64 v[102:103], v[138:139], 1, v[102:103]
	v_cvt_pk_bf16_f32 v104, v80, v81
	v_cvt_pk_bf16_f32 v105, v82, v83
	v_cvt_pk_bf16_f32 v106, v76, v77
	v_cvt_pk_bf16_f32 v107, v78, v79
	global_store_dwordx4 v[102:103], v[96:99], off
	s_nop 1
	v_mov_b32_e32 v98, v106
	v_mov_b32_e32 v96, v104
	v_mov_b32_e32 v97, v105
	v_mov_b32_e32 v99, v107
	v_permlane16_swap_b32_e32 v96, v98
	s_nop 0
	v_permlane16_swap_b32_e32 v97, v99
	s_and_saveexec_b64 s[12:13], vcc
	s_xor_b64 s[12:13], exec, s[12:13]
	v_mov_b32_e32 v99, v107
	v_mov_b32_e32 v98, v106
	s_andn2_saveexec_b64 s[12:13], s[12:13]
	v_mov_b32_e32 v96, v104
	v_mov_b32_e32 v97, v105
	s_or_b64 exec, exec, s[12:13]
	v_cvt_pk_bf16_f32 v104, v68, v69
	v_cvt_pk_bf16_f32 v105, v70, v71
	v_cvt_pk_bf16_f32 v106, v64, v65
	v_cvt_pk_bf16_f32 v107, v66, v67
	global_store_dwordx4 v[102:103], v[96:99], off offset:64
	s_nop 1
	v_mov_b32_e32 v98, v106
	v_mov_b32_e32 v96, v104
	v_mov_b32_e32 v97, v105
	v_mov_b32_e32 v99, v107
	v_permlane16_swap_b32_e32 v96, v98
	s_nop 0
	v_permlane16_swap_b32_e32 v97, v99
	s_and_saveexec_b64 s[12:13], vcc
	s_xor_b64 s[12:13], exec, s[12:13]
	v_mov_b32_e32 v99, v107
	v_mov_b32_e32 v98, v106
	s_andn2_saveexec_b64 s[12:13], s[12:13]
	v_mov_b32_e32 v96, v104
	v_mov_b32_e32 v97, v105
	s_or_b64 exec, exec, s[12:13]
	v_cvt_pk_bf16_f32 v104, v72, v73
	v_cvt_pk_bf16_f32 v105, v74, v75
	v_cvt_pk_bf16_f32 v106, v84, v85
	v_cvt_pk_bf16_f32 v107, v86, v87
	global_store_dwordx4 v[102:103], v[96:99], off offset:128
	s_nop 1
	v_mov_b32_e32 v98, v106
	v_mov_b32_e32 v96, v104
	v_mov_b32_e32 v97, v105
	v_mov_b32_e32 v99, v107
	v_permlane16_swap_b32_e32 v96, v98
	s_nop 0
	v_permlane16_swap_b32_e32 v97, v99
	s_and_saveexec_b64 s[12:13], vcc
	s_xor_b64 s[12:13], exec, s[12:13]
	v_mov_b32_e32 v99, v107
	v_mov_b32_e32 v98, v106
	s_andn2_saveexec_b64 s[12:13], s[12:13]
	v_mov_b32_e32 v96, v104
	v_mov_b32_e32 v97, v105
	s_or_b64 exec, exec, s[12:13]
	v_mul_f32_e32 v69, v69, v69
	v_fmac_f32_e32 v69, v68, v68
	v_fmac_f32_e32 v69, v70, v70
	v_mul_f32_e32 v93, v93, v93
	v_mul_f32_e32 v81, v81, v81
	v_fmac_f32_e32 v69, v71, v71
	v_fmac_f32_e32 v93, v92, v92
	v_fmac_f32_e32 v81, v80, v80
	v_fmac_f32_e32 v69, v64, v64
	v_fmac_f32_e32 v93, v94, v94
	v_fmac_f32_e32 v81, v82, v82
	v_fmac_f32_e32 v69, v65, v65
	v_mul_f32_e32 v65, v73, v73
	v_fmac_f32_e32 v93, v95, v95
	v_fmac_f32_e32 v81, v83, v83
	v_fmac_f32_e32 v65, v72, v72
	v_fmac_f32_e32 v93, v88, v88
	v_fmac_f32_e32 v81, v76, v76
	v_fmac_f32_e32 v65, v74, v74
	v_fmac_f32_e32 v93, v89, v89
	v_fmac_f32_e32 v81, v77, v77
	v_fmac_f32_e32 v65, v75, v75
	v_fmac_f32_e32 v93, v90, v90
	v_fmac_f32_e32 v81, v78, v78
	v_fmac_f32_e32 v65, v84, v84
	v_fmac_f32_e32 v93, v91, v91
	v_fmac_f32_e32 v81, v79, v79
	v_fmac_f32_e32 v69, v66, v66
	v_fmac_f32_e32 v65, v85, v85
	v_add_f32_e32 v76, v93, v81
	v_fmac_f32_e32 v69, v67, v67
	v_fmac_f32_e32 v65, v86, v86
	v_add_f32_e32 v64, v76, v69
	v_fmac_f32_e32 v65, v87, v87
	v_add_f32_e32 v64, v64, v65
	v_mov_b32_e32 v65, v64
	s_nop 1
	v_permlane16_swap_b32_e32 v64, v65
	v_add_f32_e32 v64, v64, v65
	v_mov_b32_e32 v65, v64
	s_nop 1
	v_permlane32_swap_b32_e32 v64, v65
	global_store_dwordx4 v[102:103], v[96:99], off offset:192
	s_and_saveexec_b64 s[12:13], s[4:5]
	s_cbranch_execz .LBB0_2392
	v_add_f32_e32 v66, v64, v65
	v_lshlrev_b64 v[64:65], 5, v[100:101]
	s_lshl_b32 s86, s24, 1
	s_mov_b32 s87, s45
	v_lshl_add_u64 v[64:65], s[10:11], 0, v[64:65]
	v_lshl_add_u64 v[64:65], s[86:87], 2, v[64:65]
	v_lshl_add_u64 v[64:65], v[136:137], 2, v[64:65]
	global_store_dword v[64:65], v66, off
.LBB0_2392:
	s_or_b64 exec, exec, s[12:13]
	v_cvt_pk_bf16_f32 v68, v60, v61
	v_cvt_pk_bf16_f32 v69, v62, v63
	v_cvt_pk_bf16_f32 v70, v52, v53
	v_cvt_pk_bf16_f32 v71, v54, v55
	v_mov_b32_e32 v66, v70
	v_mov_b32_e32 v64, v68
	v_mov_b32_e32 v67, v71
	v_mov_b32_e32 v65, v69
	v_permlane16_swap_b32_e32 v64, v66
	s_nop 0
	v_permlane16_swap_b32_e32 v65, v67
	s_and_saveexec_b64 s[12:13], vcc
	s_xor_b64 s[12:13], exec, s[12:13]
	v_mov_b32_e32 v67, v71
	v_mov_b32_e32 v66, v70
	s_andn2_saveexec_b64 s[12:13], s[12:13]
	v_mov_b32_e32 v64, v68
	v_mov_b32_e32 v65, v69
	s_or_b64 exec, exec, s[12:13]
	v_or_b32_e32 v68, 32, v140
	v_ashrrev_i32_e32 v69, 31, v68
	v_lshlrev_b64 v[70:71], 11, v[68:69]
	v_lshl_add_u64 v[70:71], s[8:9], 0, v[70:71]
	v_lshl_add_u64 v[70:71], s[44:45], 1, v[70:71]
	v_lshl_add_u64 v[70:71], v[138:139], 1, v[70:71]
	v_cvt_pk_bf16_f32 v72, v48, v49
	v_cvt_pk_bf16_f32 v73, v50, v51
	v_cvt_pk_bf16_f32 v74, v40, v41
	v_cvt_pk_bf16_f32 v75, v42, v43
	global_store_dwordx4 v[70:71], v[64:67], off
	s_nop 1
	v_mov_b32_e32 v64, v72
	v_mov_b32_e32 v66, v74
	v_mov_b32_e32 v65, v73
	v_mov_b32_e32 v67, v75
	v_permlane16_swap_b32_e32 v64, v66
	s_nop 0
	v_permlane16_swap_b32_e32 v65, v67
	s_and_saveexec_b64 s[12:13], vcc
	s_xor_b64 s[12:13], exec, s[12:13]
	v_mov_b32_e32 v67, v75
	v_mov_b32_e32 v66, v74
	s_andn2_saveexec_b64 s[12:13], s[12:13]
	v_mov_b32_e32 v64, v72
	v_mov_b32_e32 v65, v73
	s_or_b64 exec, exec, s[12:13]
	v_cvt_pk_bf16_f32 v72, v36, v37
	v_cvt_pk_bf16_f32 v73, v38, v39
	v_cvt_pk_bf16_f32 v74, v32, v33
	v_cvt_pk_bf16_f32 v75, v34, v35
	global_store_dwordx4 v[70:71], v[64:67], off offset:64
	s_nop 1
	v_mov_b32_e32 v64, v72
	v_mov_b32_e32 v66, v74
	v_mov_b32_e32 v65, v73
	v_mov_b32_e32 v67, v75
	v_permlane16_swap_b32_e32 v64, v66
	s_nop 0
	v_permlane16_swap_b32_e32 v65, v67
	s_and_saveexec_b64 s[12:13], vcc
	s_xor_b64 s[12:13], exec, s[12:13]
	v_mov_b32_e32 v67, v75
	v_mov_b32_e32 v66, v74
	s_andn2_saveexec_b64 s[12:13], s[12:13]
	v_mov_b32_e32 v64, v72
	v_mov_b32_e32 v65, v73
	s_or_b64 exec, exec, s[12:13]
	v_cvt_pk_bf16_f32 v72, v44, v45
	v_cvt_pk_bf16_f32 v73, v46, v47
	v_cvt_pk_bf16_f32 v74, v56, v57
	v_cvt_pk_bf16_f32 v75, v58, v59
	global_store_dwordx4 v[70:71], v[64:67], off offset:128
	s_nop 1
	v_mov_b32_e32 v64, v72
	v_mov_b32_e32 v66, v74
	v_mov_b32_e32 v65, v73
	v_mov_b32_e32 v67, v75
	v_permlane16_swap_b32_e32 v64, v66
	s_nop 0
	v_permlane16_swap_b32_e32 v65, v67
	s_and_saveexec_b64 s[12:13], vcc
	s_xor_b64 s[12:13], exec, s[12:13]
	v_mov_b32_e32 v67, v75
	v_mov_b32_e32 v66, v74
	s_andn2_saveexec_b64 s[12:13], s[12:13]
	v_mov_b32_e32 v64, v72
	v_mov_b32_e32 v65, v73
	s_or_b64 exec, exec, s[12:13]
	v_mul_f32_e32 v37, v37, v37
	v_fmac_f32_e32 v37, v36, v36
	v_fmac_f32_e32 v37, v38, v38
	v_mul_f32_e32 v61, v61, v61
	v_mul_f32_e32 v49, v49, v49
	v_fmac_f32_e32 v37, v39, v39
	v_fmac_f32_e32 v61, v60, v60
	v_fmac_f32_e32 v49, v48, v48
	v_fmac_f32_e32 v37, v32, v32
	v_fmac_f32_e32 v61, v62, v62
	v_fmac_f32_e32 v49, v50, v50
	v_fmac_f32_e32 v37, v33, v33
	v_mul_f32_e32 v33, v45, v45
	v_fmac_f32_e32 v61, v63, v63
	v_fmac_f32_e32 v49, v51, v51
	v_fmac_f32_e32 v33, v44, v44
	v_fmac_f32_e32 v61, v52, v52
	v_fmac_f32_e32 v49, v40, v40
	v_fmac_f32_e32 v33, v46, v46
	v_fmac_f32_e32 v61, v53, v53
	v_fmac_f32_e32 v49, v41, v41
	v_fmac_f32_e32 v33, v47, v47
	v_fmac_f32_e32 v61, v54, v54
	v_fmac_f32_e32 v49, v42, v42
	v_fmac_f32_e32 v33, v56, v56
	v_fmac_f32_e32 v61, v55, v55
	v_fmac_f32_e32 v49, v43, v43
	v_fmac_f32_e32 v37, v34, v34
	v_fmac_f32_e32 v33, v57, v57
	v_add_f32_e32 v40, v61, v49
	v_fmac_f32_e32 v37, v35, v35
	v_fmac_f32_e32 v33, v58, v58
	v_add_f32_e32 v32, v40, v37
	v_fmac_f32_e32 v33, v59, v59
	v_add_f32_e32 v32, v32, v33
	v_mov_b32_e32 v33, v32
	s_nop 1
	v_permlane16_swap_b32_e32 v32, v33
	v_add_f32_e32 v32, v32, v33
	v_mov_b32_e32 v33, v32
	s_nop 1
	v_permlane32_swap_b32_e32 v32, v33
	global_store_dwordx4 v[70:71], v[64:67], off offset:192
	s_and_saveexec_b64 s[12:13], s[4:5]
	s_cbranch_execz .LBB0_2410
	v_add_f32_e32 v34, v32, v33
	v_lshlrev_b64 v[32:33], 5, v[68:69]
	s_lshl_b32 s86, s24, 1
	s_mov_b32 s87, s45
	v_lshl_add_u64 v[32:33], s[10:11], 0, v[32:33]
	v_lshl_add_u64 v[32:33], s[86:87], 2, v[32:33]
	v_lshl_add_u64 v[32:33], v[136:137], 2, v[32:33]
	global_store_dword v[32:33], v34, off
.LBB0_2410:
	s_or_b64 exec, exec, s[12:13]
	v_cvt_pk_bf16_f32 v36, v24, v25
	v_cvt_pk_bf16_f32 v37, v26, v27
	v_cvt_pk_bf16_f32 v38, v20, v21
	v_cvt_pk_bf16_f32 v39, v22, v23
	v_mov_b32_e32 v34, v38
	v_mov_b32_e32 v32, v36
	v_mov_b32_e32 v33, v37
	v_mov_b32_e32 v35, v39
	v_permlane16_swap_b32_e32 v32, v34
	s_nop 0
	v_permlane16_swap_b32_e32 v33, v35
	s_and_saveexec_b64 s[12:13], vcc
	s_xor_b64 s[12:13], exec, s[12:13]
	v_mov_b32_e32 v35, v39
	v_mov_b32_e32 v34, v38
	s_andn2_saveexec_b64 s[12:13], s[12:13]
	v_mov_b32_e32 v32, v36
	v_mov_b32_e32 v33, v37
	s_or_b64 exec, exec, s[12:13]
	v_or_b32_e32 v36, 48, v140
	v_ashrrev_i32_e32 v37, 31, v36
	v_lshlrev_b64 v[38:39], 11, v[36:37]
	v_lshl_add_u64 v[38:39], s[8:9], 0, v[38:39]
	v_lshl_add_u64 v[38:39], s[44:45], 1, v[38:39]
	v_lshl_add_u64 v[38:39], v[138:139], 1, v[38:39]
	v_cvt_pk_bf16_f32 v40, v12, v13
	v_cvt_pk_bf16_f32 v41, v14, v15
	v_cvt_pk_bf16_f32 v42, v8, v9
	v_cvt_pk_bf16_f32 v43, v10, v11
	global_store_dwordx4 v[38:39], v[32:35], off
	s_nop 1
	v_mov_b32_e32 v32, v40
	v_mov_b32_e32 v34, v42
	v_mov_b32_e32 v35, v43
	v_mov_b32_e32 v33, v41
	v_permlane16_swap_b32_e32 v32, v34
	s_nop 0
	v_permlane16_swap_b32_e32 v33, v35
	s_and_saveexec_b64 s[12:13], vcc
	s_xor_b64 s[12:13], exec, s[12:13]
	v_mov_b32_e32 v35, v43
	v_mov_b32_e32 v34, v42
	s_andn2_saveexec_b64 s[12:13], s[12:13]
	v_mov_b32_e32 v32, v40
	v_mov_b32_e32 v33, v41
	s_or_b64 exec, exec, s[12:13]
	v_cvt_pk_bf16_f32 v40, v4, v5
	v_cvt_pk_bf16_f32 v41, v6, v7
	v_cvt_pk_bf16_f32 v42, v0, v1
	v_cvt_pk_bf16_f32 v43, v2, v3
	global_store_dwordx4 v[38:39], v[32:35], off offset:64
	s_nop 1
	v_mov_b32_e32 v32, v40
	v_mov_b32_e32 v34, v42
	v_mov_b32_e32 v35, v43
	v_mov_b32_e32 v33, v41
	v_permlane16_swap_b32_e32 v32, v34
	s_nop 0
	v_permlane16_swap_b32_e32 v33, v35
	s_and_saveexec_b64 s[12:13], vcc
	s_xor_b64 s[12:13], exec, s[12:13]
	v_mov_b32_e32 v35, v43
	v_mov_b32_e32 v34, v42
	s_andn2_saveexec_b64 s[12:13], s[12:13]
	v_mov_b32_e32 v32, v40
	v_mov_b32_e32 v33, v41
	s_or_b64 exec, exec, s[12:13]
	v_cvt_pk_bf16_f32 v40, v16, v17
	v_cvt_pk_bf16_f32 v41, v18, v19
	v_cvt_pk_bf16_f32 v42, v28, v29
	v_cvt_pk_bf16_f32 v43, v30, v31
	global_store_dwordx4 v[38:39], v[32:35], off offset:128
	s_nop 1
	v_mov_b32_e32 v32, v40
	v_mov_b32_e32 v34, v42
	v_mov_b32_e32 v35, v43
	v_mov_b32_e32 v33, v41
	v_permlane16_swap_b32_e32 v32, v34
	s_nop 0
	v_permlane16_swap_b32_e32 v33, v35
	s_and_saveexec_b64 s[12:13], vcc
	s_xor_b64 s[12:13], exec, s[12:13]
	v_mov_b32_e32 v35, v43
	v_mov_b32_e32 v34, v42
	s_andn2_saveexec_b64 s[12:13], s[12:13]
	v_mov_b32_e32 v32, v40
	v_mov_b32_e32 v33, v41
	s_or_b64 exec, exec, s[12:13]
	v_mul_f32_e32 v5, v5, v5
	v_fmac_f32_e32 v5, v4, v4
	v_fmac_f32_e32 v5, v6, v6
	v_mul_f32_e32 v25, v25, v25
	v_mul_f32_e32 v13, v13, v13
	v_fmac_f32_e32 v5, v7, v7
	v_fmac_f32_e32 v25, v24, v24
	v_fmac_f32_e32 v13, v12, v12
	v_fmac_f32_e32 v5, v0, v0
	v_fmac_f32_e32 v25, v26, v26
	v_fmac_f32_e32 v13, v14, v14
	v_fmac_f32_e32 v5, v1, v1
	v_mul_f32_e32 v1, v17, v17
	v_fmac_f32_e32 v25, v27, v27
	v_fmac_f32_e32 v13, v15, v15
	v_fmac_f32_e32 v1, v16, v16
	v_fmac_f32_e32 v25, v20, v20
	v_fmac_f32_e32 v13, v8, v8
	v_fmac_f32_e32 v1, v18, v18
	v_fmac_f32_e32 v25, v21, v21
	v_fmac_f32_e32 v13, v9, v9
	v_fmac_f32_e32 v1, v19, v19
	v_fmac_f32_e32 v25, v22, v22
	v_fmac_f32_e32 v13, v10, v10
	v_fmac_f32_e32 v1, v28, v28
	v_fmac_f32_e32 v25, v23, v23
	v_fmac_f32_e32 v13, v11, v11
	v_fmac_f32_e32 v5, v2, v2
	v_fmac_f32_e32 v1, v29, v29
	v_add_f32_e32 v8, v25, v13
	v_fmac_f32_e32 v5, v3, v3
	v_fmac_f32_e32 v1, v30, v30
	v_add_f32_e32 v0, v8, v5
	v_fmac_f32_e32 v1, v31, v31
	v_add_f32_e32 v0, v0, v1
	v_mov_b32_e32 v1, v0
	s_nop 1
	v_permlane16_swap_b32_e32 v0, v1
	v_add_f32_e32 v0, v0, v1
	v_mov_b32_e32 v1, v0
	s_nop 1
	v_permlane32_swap_b32_e32 v0, v1
	global_store_dwordx4 v[38:39], v[32:35], off offset:192
	s_and_saveexec_b64 s[12:13], s[4:5]
	s_xor_b64 s[4:5], exec, s[12:13]
	s_cbranch_execz .LBB0_2345
	v_add_f32_e32 v2, v0, v1
	v_lshlrev_b64 v[0:1], 5, v[36:37]
	s_lshl_b32 s44, s24, 1
	v_lshl_add_u64 v[0:1], s[10:11], 0, v[0:1]
	v_lshl_add_u64 v[0:1], s[44:45], 2, v[0:1]
	v_lshl_add_u64 v[0:1], v[136:137], 2, v[0:1]
	global_store_dword v[0:1], v2, off
	s_branch .LBB0_2345
